# up-GEMM epilogue: removed the 256 dead v_mov vX,0 that hipcc emits as the unused old operand of full-mask row_ror DPP moves (s_nop kept where a slot covered a hazard distance)
# speedup vs baseline: 1.0067x; 1.0067x over previous
; #define PG8_LAS __attribute__((address_space(3)))
;     __device__ __forceinline__ void operator()(const f32x4 (&acc)[2][2][4][2], const Unit& u, int wr, int wc, int fr, int fq) const {
;     ...
;             for (int m = 0; m < 4; ++m) r2v[ai][m] = rsqrtf(r2v[ai][m] * (1.f / 2048.f) + 1e-6f);
;         if (fr >= 14) {
; #pragma unroll
;             for (int ai = 0; ai < 2; ++ai)
; #pragma unroll
;                 for (int bj = 0; bj < 2; ++bj)
; #pragma unroll
;                     for (int n = 0; n < 2; ++n) *(PG8_LAS f32x4*)(xch + (((ai * 2 + wr) * 2 + (fr - 14)) * 256 + bj * 128 + colx + n * 4)) = acc[ai][bj][3][n] * r2v[ai][3];
;         }
;         asm volatile("s_waitcnt lgkmcnt(0)" ::: "memory"); __builtin_amdgcn_s_barrier(); asm volatile("" ::: "memory");
;         const bool first = (ti == 0);
;         const f32x4 zero4 = (f32x4){0.f, 0.f, 0.f, 0.f};
; #pragma unroll
;         for (int n = 0; n < 2; ++n) {
;             const f32x4 w0[2] = {wts[n][0][0], wts[n][1][0]}, w1[2] = {wts[n][0][1], wts[n][1][1]}, w2[2] = {wts[n][0][2], wts[n][1][2]}, bb[2] = {wts[n][0][3], wts[n][1][3]};
; #pragma unroll
;             for (int ai = 0; ai < 2; ++ai) {
;                 f32x4 pr1[2] = {zero4, zero4}, pr2[2] = {zero4, zero4};
;                 const bool hasprev = (wr == 1) || (ai == 1);
;                 const int pg = (wr == 1) ? ai * 2 : (ai - 1) * 2 + 1;
;                 if (hasprev && fr < 2) {
; #pragma unroll
;                     for (int bj = 0; bj < 2; ++bj) {
;                         pr2[bj] = *(const PG8_LAS f32x4*)(xch + ((pg * 2 + fr) * 256 + bj * 128 + colx + n * 4));
;                         pr1[bj] = *(const PG8_LAS f32x4*)(xch + ((pg * 2 + 1) * 256 + bj * 128 + colx + n * 4)); }
;                 }
; #pragma unroll
;                 for (int m = 0; m < 4; ++m) {
;                     f32x4 cur[2] = {acc[ai][0][m][n] * r2v[ai][m], acc[ai][1][m][n] * r2v[ai][m]};
;                     if (first && ai == 0 && wr == 0 && m == 0 && fr < 2) { cur[0] = zero4; cur[1] = zero4; }
;                     f32x4 r1[2], r2[2], av[2];
; #pragma unroll
;                     for (int bj = 0; bj < 2; ++bj)
; #pragma unroll
;                         for (int e = 0; e < 4; ++e) { r1[bj][e] = dpp_ror1(cur[bj][e]); r2[bj][e] = dpp_ror2(cur[bj][e]); }
; #pragma unroll
;                     for (int bj = 0; bj < 2; ++bj)
; #pragma unroll
.LBB0_896:
	s_or_b64 exec, exec, s[0:1]
	v_fmamk_f32 v198, v198, 0x3a000000, v224
	v_mul_f32_e32 v199, 0x4b800000, v198
	v_cmp_gt_f32_e32 vcc, s35, v198
	s_or_b32 s0, s65, s92
	s_cmp_eq_u32 s0, 0
	v_cndmask_b32_e32 v198, v198, v199, vcc
	v_rsq_f32_e32 v198, v198
	s_cselect_b64 s[0:1], -1, 0
	s_and_b64 s[78:79], s[0:1], s[6:7]
	v_mul_f32_e32 v199, 0x45800000, v198
	v_cndmask_b32_e32 v204, v198, v199, vcc
	v_pk_mul_f32 v[100:101], v[100:101], v[204:205] op_sel_hi:[1,0]
	v_pk_mul_f32 v[96:97], v[96:97], v[204:205] op_sel_hi:[1,0]
	v_pk_mul_f32 v[98:99], v[98:99], v[204:205] op_sel_hi:[1,0]
	v_cndmask_b32_e64 v241, v96, 0, s[78:79]
	v_cndmask_b32_e64 v96, v100, 0, s[78:79]
	v_pk_mul_f32 v[102:103], v[102:103], v[204:205] op_sel_hi:[1,0]
	v_cndmask_b32_e64 v200, v98, 0, s[78:79]
	v_cndmask_b32_e64 v98, v101, 0, s[78:79]
	v_mov_b32_dpp v238, v96 row_ror:1 row_mask:0xf bank_mask:0xf
	v_cndmask_b32_e64 v102, v102, 0, s[78:79]
	v_mov_b32_dpp v239, v96 row_ror:2 row_mask:0xf bank_mask:0xf
	v_mov_b32_dpp v236, v98 row_ror:1 row_mask:0xf bank_mask:0xf
	s_waitcnt lgkmcnt(1)
	v_cndmask_b32_e64 v100, v238, v168, s[8:9]
	v_fma_f32 v96, v148, v96, v152
	v_cndmask_b32_e64 v242, v103, 0, s[78:79]
	v_mov_b32_dpp v237, v98 row_ror:2 row_mask:0xf bank_mask:0xf
	v_mov_b32_dpp v234, v102 row_ror:1 row_mask:0xf bank_mask:0xf
	v_cndmask_b32_e64 v168, v172, v239, s[10:11]
	v_fma_f32 v96, v144, v100, v96
	v_cndmask_b32_e64 v100, v236, v169, s[8:9]
	v_fma_f32 v98, v149, v98, v153
	v_mov_b32_dpp v235, v102 row_ror:2 row_mask:0xf bank_mask:0xf
	v_mov_b32_dpp v232, v242 row_ror:1 row_mask:0xf bank_mask:0xf
	v_fma_f32 v96, v136, v168, v96
	v_cndmask_b32_e64 v168, v173, v237, s[10:11]
	v_fma_f32 v98, v145, v100, v98
	v_cndmask_b32_e64 v100, v234, v170, s[8:9]
	v_fma_f32 v102, v150, v102, v154
	v_mov_b32_dpp v233, v242 row_ror:2 row_mask:0xf bank_mask:0xf
	v_fma_f32 v98, v137, v168, v98
	v_cndmask_b32_e64 v168, v174, v235, s[10:11]
	v_fma_f32 v100, v146, v100, v102
	v_cndmask_b32_e64 v102, v232, v171, s[8:9]
	v_mov_b32_dpp v230, v241 row_ror:1 row_mask:0xf bank_mask:0xf
	v_fma_f32 v100, v138, v168, v100
	v_cndmask_b32_e64 v168, v175, v233, s[10:11]
	v_fma_f32 v169, v151, v242, v155
	v_cndmask_b32_e64 v240, v97, 0, s[78:79]
	v_fma_f32 v102, v147, v102, v169
	v_mov_b32_dpp v231, v241 row_ror:2 row_mask:0xf bank_mask:0xf
	v_fma_f32 v168, v139, v168, v102
	s_waitcnt lgkmcnt(0)
	v_cndmask_b32_e64 v102, v230, v160, s[8:9]
	v_mov_b32_dpp v198, v240 row_ror:1 row_mask:0xf bank_mask:0xf
	v_cndmask_b32_e64 v160, v164, v231, s[10:11]
	v_fma_f32 v164, v128, v241, v132
	v_mov_b32_dpp v227, v240 row_ror:2 row_mask:0xf bank_mask:0xf
	v_fma_f32 v102, v124, v102, v164
	v_fma_f32 v102, v120, v160, v102
	v_cndmask_b32_e64 v160, v198, v161, s[8:9]
	v_mov_b32_dpp v101, v200 row_ror:1 row_mask:0xf bank_mask:0xf
	v_cndmask_b32_e64 v161, v165, v227, s[10:11]
	v_fma_f32 v164, v129, v240, v133
	v_cndmask_b32_e64 v199, v99, 0, s[78:79]
	v_fma_f32 v160, v125, v160, v164
	v_mov_b32_dpp v103, v200 row_ror:2 row_mask:0xf bank_mask:0xf
	v_fma_f32 v160, v121, v161, v160
	v_cndmask_b32_e64 v161, v101, v162, s[8:9]
	v_cndmask_b32_e64 v162, v166, v103, s[10:11]
	v_mov_b32_dpp v97, v199 row_ror:1 row_mask:0xf bank_mask:0xf
	v_fma_f32 v164, v130, v200, v134
	v_fma_f32 v161, v126, v161, v164
	v_cmp_gt_i32_e32 vcc, s68, v201
	v_fma_f32 v161, v122, v162, v161
	v_cndmask_b32_e64 v162, v97, v163, s[8:9]
	v_mov_b32_dpp v99, v199 row_ror:2 row_mask:0xf bank_mask:0xf
	v_fma_f32 v164, v131, v199, v135
	s_and_b64 s[80:81], s[46:47], vcc
	v_fma_f32 v162, v127, v162, v164
	v_add_u32_e32 v199, s59, v201
	v_cndmask_b32_e64 v163, v167, v99, s[10:11]
	v_fma_f32 v162, v123, v163, v162
	s_and_saveexec_b64 s[0:1], s[80:81]
	s_cbranch_execz .LBB0_898
	v_mul_f32_e32 v163, 0xbfb8aa3b, v168
	v_exp_f32_e32 v163, v163
	v_mul_f32_e32 v164, 0xbfb8aa3b, v100
	v_exp_f32_e32 v164, v164
	v_mul_f32_e32 v165, 0xbfb8aa3b, v98
	v_add_f32_e32 v163, 1.0, v163
	v_rcp_f32_e32 v163, v163
	v_add_f32_e32 v164, 1.0, v164
	v_exp_f32_e32 v165, v165
	v_rcp_f32_e32 v164, v164
	v_mul_f32_e32 v163, v168, v163
	v_mul_f32_e32 v162, v163, v162
	v_mul_f32_e32 v163, 0xbfb8aa3b, v96
	v_exp_f32_e32 v163, v163
	v_mul_f32_e32 v100, v100, v164
	v_add_f32_e32 v164, 1.0, v165
	v_rcp_f32_e32 v164, v164
	v_add_f32_e32 v163, 1.0, v163
	v_rcp_f32_e32 v163, v163
	v_mul_f32_e32 v100, v100, v161
	v_mul_f32_e32 v98, v98, v164
	v_mul_f32_e32 v98, v98, v160
	v_mul_f32_e32 v96, v96, v163
	v_mul_f32_e32 v96, v96, v102
	v_cvt_pk_bf16_f32 v160, v96, v98
	v_cvt_pk_bf16_f32 v161, v100, v162
	v_mov_b64_e32 v[162:163], s[36:37]
	v_mad_i64_i32 v[162:163], s[64:65], v199, s69, v[162:163]
	v_lshl_add_u64 v[162:163], v[192:193], 1, v[162:163]
	global_store_dwordx2 v[162:163], v[160:161], off
; __device__ __forceinline__ unsigned cvt_pk_bf16(float lo, float hi) { unsigned r; asm volatile("v_cvt_pk_bf16_f32 %0, %1, %2" : "=v"(r) : "v"(lo), "v"(hi)); return r; }
; __device__ __forceinline__ float sigmoid_f(float x) { return __builtin_amdgcn_rcpf(1.0f + __builtin_amdgcn_exp2f(-1.4426950408889634f * x)); }
; __device__ __forceinline__ float dpp_ror1(float v) { return __builtin_bit_cast(float, __builtin_amdgcn_update_dpp(0, __builtin_bit_cast(int, v), 0x121, 0xf, 0xf, false)); }
; __device__ __forceinline__ float dpp_ror2(float v) { return __builtin_bit_cast(float, __builtin_amdgcn_update_dpp(0, __builtin_bit_cast(int, v), 0x122, 0xf, 0xf, false)); }
; __device__ __forceinline__ float fma_s(float a, float b, float c) { float r; asm("v_fma_f32 %0, %1, %2, %3" : "=v"(r) : "v"(a), "v"(b), "v"(c)); return r; }
;     __device__ __forceinline__ void operator()(const f32x4 (&acc)[2][2][4][2], const Unit& u, int wr, int wc, int fr, int fq) const {
;     ...
;                 for (int m = 0; m < 4; ++m) {
;                     f32x4 cur[2] = {acc[ai][0][m][n] * r2v[ai][m], acc[ai][1][m][n] * r2v[ai][m]};
;                     if (first && ai == 0 && wr == 0 && m == 0 && fr < 2) { cur[0] = zero4; cur[1] = zero4; }
;                     f32x4 r1[2], r2[2], av[2];
; #pragma unroll
;                     for (int bj = 0; bj < 2; ++bj)
; #pragma unroll
;                         for (int e = 0; e < 4; ++e) { r1[bj][e] = dpp_ror1(cur[bj][e]); r2[bj][e] = dpp_ror2(cur[bj][e]); }
; #pragma unroll
;                     for (int bj = 0; bj < 2; ++bj)
; #pragma unroll
;                         for (int e = 0; e < 4; ++e) { const float p1 = fr >= 1 ? r1[bj][e] : pr1[bj][e], p2 = fr >= 2 ? r2[bj][e] : pr2[bj][e];
;                             av[bj][e] = fma_s(w0[bj][e], p2, fma_s(w1[bj][e], p1, fma_s(w2[bj][e], cur[bj][e], bb[bj][e]))); }
;                     float o[4];
; #pragma unroll
;                     for (int e = 0; e < 4; ++e) o[e] = av[0][e] * sigmoid_f(av[0][e]) * av[1][e];
;                     const int lr = ai * HALF + wr * 64 + m * 16 + fr, t = t0 + lr;
;                     if (lr >= 2 && t < 4096) { u32x2 w; w.x = cvt_pk_bf16(o[0], o[1]); w.y = cvt_pk_bf16(o[2], o[3]);
;                         *(u32x2*)(gout + (size_t)(b * 4096 + t) * FF + j0 + n * 4) = w; }
;                     pr1[0] = r1[0]; pr1[1] = r1[1]; pr2[0] = r2[0]; pr2[1] = r2[1];
.LBB0_898:
	s_or_b64 exec, exec, s[0:1]
	v_fmamk_f32 v96, v197, 0x3a000000, v224
	v_mul_f32_e32 v98, 0x4b800000, v96
	v_cmp_gt_f32_e32 vcc, s35, v96
	s_nop 1
	v_cndmask_b32_e32 v96, v96, v98, vcc
	v_rsq_f32_e32 v96, v96
	s_nop 0
	v_mul_f32_e32 v98, 0x45800000, v96
	v_cndmask_b32_e32 v200, v96, v98, vcc
	v_pk_mul_f32 v[92:93], v[92:93], v[200:201] op_sel_hi:[1,0]
	v_pk_mul_f32 v[174:175], v[88:89], v[200:201] op_sel_hi:[1,0]
	v_pk_mul_f32 v[172:173], v[90:91], v[200:201] op_sel_hi:[1,0]
	v_mov_b32_dpp v170, v92 row_ror:1 row_mask:0xf bank_mask:0xf
	v_mov_b32_dpp v171, v92 row_ror:2 row_mask:0xf bank_mask:0xf
	v_cndmask_b32_e64 v88, v170, v238, s[8:9]
	v_mov_b32_dpp v168, v93 row_ror:1 row_mask:0xf bank_mask:0xf
	v_cndmask_b32_e64 v89, v239, v171, s[10:11]
	v_fma_f32 v90, v148, v92, v152
	v_pk_mul_f32 v[94:95], v[94:95], v[200:201] op_sel_hi:[1,0]
	v_fma_f32 v88, v144, v88, v90
	v_mov_b32_dpp v169, v93 row_ror:2 row_mask:0xf bank_mask:0xf
	v_fma_f32 v88, v136, v89, v88
	v_cndmask_b32_e64 v89, v168, v236, s[8:9]
	v_mov_b32_dpp v166, v94 row_ror:1 row_mask:0xf bank_mask:0xf
	v_cndmask_b32_e64 v90, v237, v169, s[10:11]
	v_fma_f32 v91, v149, v93, v153
	v_fma_f32 v89, v145, v89, v91
	v_mov_b32_dpp v167, v94 row_ror:2 row_mask:0xf bank_mask:0xf
	v_fma_f32 v89, v137, v90, v89
	v_cndmask_b32_e64 v90, v166, v234, s[8:9]
	v_mov_b32_dpp v163, v95 row_ror:1 row_mask:0xf bank_mask:0xf
	v_cndmask_b32_e64 v91, v235, v167, s[10:11]
	v_fma_f32 v92, v150, v94, v154
	v_fma_f32 v90, v146, v90, v92
	v_mov_b32_dpp v165, v95 row_ror:2 row_mask:0xf bank_mask:0xf
	v_fma_f32 v90, v138, v91, v90
	v_cndmask_b32_e64 v91, v163, v232, s[8:9]
	v_mov_b32_dpp v162, v174 row_ror:1 row_mask:0xf bank_mask:0xf
	v_cndmask_b32_e64 v92, v233, v165, s[10:11]
	v_fma_f32 v93, v151, v95, v155
	v_fma_f32 v91, v147, v91, v93
	v_mov_b32_dpp v164, v174 row_ror:2 row_mask:0xf bank_mask:0xf
	v_fma_f32 v92, v139, v92, v91
	v_cndmask_b32_e64 v91, v162, v230, s[8:9]
	v_mov_b32_dpp v160, v175 row_ror:1 row_mask:0xf bank_mask:0xf
	v_cndmask_b32_e64 v93, v231, v164, s[10:11]
	v_fma_f32 v94, v128, v174, v132
	v_fma_f32 v91, v124, v91, v94
	v_mov_b32_dpp v161, v175 row_ror:2 row_mask:0xf bank_mask:0xf
	v_fma_f32 v91, v120, v93, v91
	v_cndmask_b32_e64 v93, v160, v198, s[8:9]
	v_mov_b32_dpp v100, v172 row_ror:1 row_mask:0xf bank_mask:0xf
	v_cndmask_b32_e64 v94, v227, v161, s[10:11]
	v_fma_f32 v95, v129, v175, v133
	v_fma_f32 v93, v125, v93, v95
	v_mov_b32_dpp v102, v172 row_ror:2 row_mask:0xf bank_mask:0xf
	v_fma_f32 v93, v121, v94, v93
	v_cndmask_b32_e64 v94, v100, v101, s[8:9]
	v_mov_b32_dpp v96, v173 row_ror:1 row_mask:0xf bank_mask:0xf
	v_cndmask_b32_e64 v95, v103, v102, s[10:11]
	v_fma_f32 v101, v130, v172, v134
	s_nop 0
	v_fma_f32 v94, v126, v94, v101
	v_mov_b32_dpp v98, v173 row_ror:2 row_mask:0xf bank_mask:0xf
	v_fma_f32 v94, v122, v95, v94
	v_cndmask_b32_e64 v95, v96, v97, s[8:9]
	v_cndmask_b32_e64 v97, v99, v98, s[10:11]
	v_fma_f32 v99, v131, v173, v135
	s_nop 0
	v_fma_f32 v95, v127, v95, v99
	s_nop 0
	v_fma_f32 v95, v123, v97, v95
	v_add_u32_e32 v97, s71, v212
	v_cmp_gt_i32_e32 vcc, s68, v97
	s_and_b64 s[66:67], s[52:53], vcc
	v_add_u32_e32 v197, s59, v97
	s_and_saveexec_b64 s[0:1], s[66:67]
	s_cbranch_execz .LBB0_900
	v_mul_f32_e32 v97, 0xbfb8aa3b, v92
	v_exp_f32_e32 v97, v97
	v_mul_f32_e32 v99, 0xbfb8aa3b, v90
	v_mul_f32_e32 v101, 0xbfb8aa3b, v89
	v_exp_f32_e32 v99, v99
	v_add_f32_e32 v97, 1.0, v97
	v_rcp_f32_e32 v97, v97
	v_exp_f32_e32 v101, v101
	v_add_f32_e32 v99, 1.0, v99
	v_rcp_f32_e32 v99, v99
	v_mul_f32_e32 v92, v92, v97
	v_mul_f32_e32 v92, v92, v95
	v_mul_f32_e32 v95, 0xbfb8aa3b, v88
	v_exp_f32_e32 v95, v95
	v_add_f32_e32 v97, 1.0, v101
	v_rcp_f32_e32 v97, v97
	v_mul_f32_e32 v90, v90, v99
	v_add_f32_e32 v95, 1.0, v95
	v_rcp_f32_e32 v95, v95
	v_mul_f32_e32 v89, v89, v97
	v_mul_f32_e32 v90, v90, v94
	v_mul_f32_e32 v89, v89, v93
	v_mul_f32_e32 v88, v88, v95
	v_mul_f32_e32 v88, v88, v91
	v_cvt_pk_bf16_f32 v88, v88, v89
	v_cvt_pk_bf16_f32 v89, v90, v92
	v_mov_b64_e32 v[90:91], s[36:37]
	v_mad_i64_i32 v[90:91], s[64:65], v197, s69, v[90:91]
	v_lshl_add_u64 v[90:91], v[192:193], 1, v[90:91]
	global_store_dwordx2 v[90:91], v[88:89], off
.LBB0_900:
	s_or_b64 exec, exec, s[0:1]
	v_fmamk_f32 v88, v195, 0x3a000000, v224
	v_mul_f32_e32 v89, 0x4b800000, v88
	v_cmp_gt_f32_e32 vcc, s35, v88
	s_nop 1
	v_cndmask_b32_e32 v88, v88, v89, vcc
	v_rsq_f32_e32 v88, v88
	s_nop 0
	v_mul_f32_e32 v89, 0x45800000, v88
	v_cndmask_b32_e32 v198, v88, v89, vcc
	v_pk_mul_f32 v[174:175], v[84:85], v[198:199] op_sel_hi:[1,0]
	v_pk_mul_f32 v[172:173], v[86:87], v[198:199] op_sel_hi:[1,0]
	v_fma_f32 v101, v148, v174, v152
	v_fma_f32 v103, v149, v175, v153
	v_mov_b32_dpp v94, v174 row_ror:1 row_mask:0xf bank_mask:0xf
	v_mov_b32_dpp v95, v174 row_ror:2 row_mask:0xf bank_mask:0xf
	v_cndmask_b32_e64 v97, v94, v170, s[8:9]
	v_mov_b32_dpp v92, v175 row_ror:1 row_mask:0xf bank_mask:0xf
	v_cndmask_b32_e64 v99, v171, v95, s[10:11]
	v_fma_f32 v97, v144, v97, v101
	v_mov_b32_dpp v93, v175 row_ror:2 row_mask:0xf bank_mask:0xf
	v_fma_f32 v97, v136, v99, v97
	v_cndmask_b32_e64 v99, v92, v168, s[8:9]
	v_mov_b32_dpp v90, v172 row_ror:1 row_mask:0xf bank_mask:0xf
	v_cndmask_b32_e64 v101, v169, v93, s[10:11]
	v_fma_f32 v99, v145, v99, v103
	v_fma_f32 v101, v137, v101, v99
	v_cndmask_b32_e64 v99, v90, v166, s[8:9]
	v_mov_b32_dpp v91, v172 row_ror:2 row_mask:0xf bank_mask:0xf
	v_mov_b32_dpp v87, v173 row_ror:1 row_mask:0xf bank_mask:0xf
	v_fma_f32 v166, v150, v172, v154
	v_pk_mul_f32 v[232:233], v[80:81], v[198:199] op_sel_hi:[1,0]
	v_fma_f32 v99, v146, v99, v166
	v_cndmask_b32_e64 v103, v167, v91, s[10:11]
	v_fma_f32 v166, v138, v103, v99
; __device__ __forceinline__ unsigned cvt_pk_bf16(float lo, float hi) { unsigned r; asm volatile("v_cvt_pk_bf16_f32 %0, %1, %2" : "=v"(r) : "v"(lo), "v"(hi)); return r; }
; __device__ __forceinline__ float sigmoid_f(float x) { return __builtin_amdgcn_rcpf(1.0f + __builtin_amdgcn_exp2f(-1.4426950408889634f * x)); }
; __device__ __forceinline__ float dpp_ror1(float v) { return __builtin_bit_cast(float, __builtin_amdgcn_update_dpp(0, __builtin_bit_cast(int, v), 0x121, 0xf, 0xf, false)); }
; __device__ __forceinline__ float dpp_ror2(float v) { return __builtin_bit_cast(float, __builtin_amdgcn_update_dpp(0, __builtin_bit_cast(int, v), 0x122, 0xf, 0xf, false)); }
; __device__ __forceinline__ float fma_s(float a, float b, float c) { float r; asm("v_fma_f32 %0, %1, %2, %3" : "=v"(r) : "v"(a), "v"(b), "v"(c)); return r; }
;     __device__ __forceinline__ void operator()(const f32x4 (&acc)[2][2][4][2], const Unit& u, int wr, int wc, int fr, int fq) const {
;     ...
;                 for (int m = 0; m < 4; ++m) {
;                     f32x4 cur[2] = {acc[ai][0][m][n] * r2v[ai][m], acc[ai][1][m][n] * r2v[ai][m]};
;                     if (first && ai == 0 && wr == 0 && m == 0 && fr < 2) { cur[0] = zero4; cur[1] = zero4; }
;                     f32x4 r1[2], r2[2], av[2];
; #pragma unroll
;                     for (int bj = 0; bj < 2; ++bj)
; #pragma unroll
;                         for (int e = 0; e < 4; ++e) { r1[bj][e] = dpp_ror1(cur[bj][e]); r2[bj][e] = dpp_ror2(cur[bj][e]); }
; #pragma unroll
;                     for (int bj = 0; bj < 2; ++bj)
; #pragma unroll
;                         for (int e = 0; e < 4; ++e) { const float p1 = fr >= 1 ? r1[bj][e] : pr1[bj][e], p2 = fr >= 2 ? r2[bj][e] : pr2[bj][e];
;                             av[bj][e] = fma_s(w0[bj][e], p2, fma_s(w1[bj][e], p1, fma_s(w2[bj][e], cur[bj][e], bb[bj][e]))); }
;                     float o[4];
; #pragma unroll
;                     for (int e = 0; e < 4; ++e) o[e] = av[0][e] * sigmoid_f(av[0][e]) * av[1][e];
;                     const int lr = ai * HALF + wr * 64 + m * 16 + fr, t = t0 + lr;
;                     if (lr >= 2 && t < 4096) { u32x2 w; w.x = cvt_pk_bf16(o[0], o[1]); w.y = cvt_pk_bf16(o[2], o[3]);
;                         *(u32x2*)(gout + (size_t)(b * 4096 + t) * FF + j0 + n * 4) = w; }
;                     pr1[0] = r1[0]; pr1[1] = r1[1]; pr2[0] = r2[0]; pr2[1] = r2[1];
	v_cndmask_b32_e64 v99, v87, v163, s[8:9]
	v_mov_b32_dpp v89, v173 row_ror:2 row_mask:0xf bank_mask:0xf
	v_mov_b32_dpp v86, v232 row_ror:1 row_mask:0xf bank_mask:0xf
	v_fma_f32 v163, v151, v173, v155
	v_fma_f32 v99, v147, v99, v163
	v_cndmask_b32_e64 v103, v165, v89, s[10:11]
	v_mov_b32_dpp v88, v232 row_ror:2 row_mask:0xf bank_mask:0xf
	v_fma_f32 v163, v139, v103, v99
	v_cndmask_b32_e64 v99, v86, v162, s[8:9]
	v_pk_mul_f32 v[230:231], v[82:83], v[198:199] op_sel_hi:[1,0]
	v_mov_b32_dpp v84, v233 row_ror:1 row_mask:0xf bank_mask:0xf
	v_cndmask_b32_e64 v103, v164, v88, s[10:11]
	v_fma_f32 v162, v128, v232, v132
	v_mov_b32_dpp v85, v233 row_ror:2 row_mask:0xf bank_mask:0xf
	v_fma_f32 v99, v124, v99, v162
	v_mov_b32_dpp v82, v230 row_ror:1 row_mask:0xf bank_mask:0xf
	v_fma_f32 v99, v120, v103, v99
	v_cndmask_b32_e64 v103, v84, v160, s[8:9]
	v_mov_b32_dpp v83, v230 row_ror:2 row_mask:0xf bank_mask:0xf
	v_mov_b32_dpp v80, v231 row_ror:1 row_mask:0xf bank_mask:0xf
	v_cndmask_b32_e64 v160, v161, v85, s[10:11]
	v_fma_f32 v161, v129, v233, v133
	v_cndmask_b32_e64 v100, v82, v100, s[8:9]
	v_fma_f32 v103, v125, v103, v161
	v_mov_b32_dpp v81, v231 row_ror:2 row_mask:0xf bank_mask:0xf
	v_fma_f32 v103, v121, v160, v103
	v_cndmask_b32_e64 v102, v102, v83, s[10:11]
	v_fma_f32 v160, v130, v230, v134
	v_cndmask_b32_e64 v96, v80, v96, s[8:9]
	v_fma_f32 v100, v126, v100, v160
	v_cndmask_b32_e64 v98, v98, v81, s[10:11]
	v_fma_f32 v100, v122, v102, v100
	v_fma_f32 v102, v131, v231, v135
	s_nop 0
	v_fma_f32 v96, v127, v96, v102
	s_nop 0
	v_fma_f32 v96, v123, v98, v96
	v_add_u32_e32 v98, s71, v213
	v_cmp_gt_i32_e32 vcc, s68, v98
	s_and_b64 s[0:1], s[52:53], vcc
	v_add_u32_e32 v195, s59, v98
	s_and_saveexec_b64 s[64:65], s[0:1]
	s_cbranch_execz .LBB0_902
	v_mul_f32_e32 v98, 0xbfb8aa3b, v163
	v_exp_f32_e32 v98, v98
	s_nop 0
	v_add_f32_e32 v98, 1.0, v98
	v_rcp_f32_e32 v98, v98
	s_nop 0
	v_mul_f32_e32 v98, v163, v98
	v_mul_f32_e32 v98, v98, v96
	v_mul_f32_e32 v96, 0xbfb8aa3b, v166
	v_exp_f32_e32 v96, v96
	s_nop 0
	v_add_f32_e32 v96, 1.0, v96
	v_rcp_f32_e32 v96, v96
	s_nop 0
	v_mul_f32_e32 v96, v166, v96
	v_mul_f32_e32 v100, v96, v100
	v_mul_f32_e32 v96, 0xbfb8aa3b, v101
	v_exp_f32_e32 v96, v96
	s_nop 0
	v_add_f32_e32 v96, 1.0, v96
	v_rcp_f32_e32 v96, v96
	s_nop 0
	v_mul_f32_e32 v96, v101, v96
	v_mul_f32_e32 v101, 0xbfb8aa3b, v97
	v_exp_f32_e32 v101, v101
	v_mul_f32_e32 v96, v96, v103
	v_add_f32_e32 v101, 1.0, v101
	v_rcp_f32_e32 v101, v101
	s_nop 0
	v_mul_f32_e32 v97, v97, v101
	v_mul_f32_e32 v97, v97, v99
	v_cvt_pk_bf16_f32 v96, v97, v96
	v_cvt_pk_bf16_f32 v97, v100, v98
	v_mov_b64_e32 v[98:99], s[36:37]
	v_mad_i64_i32 v[98:99], s[72:73], v195, s69, v[98:99]
	v_lshl_add_u64 v[98:99], v[192:193], 1, v[98:99]
	global_store_dwordx2 v[98:99], v[96:97], off
.LBB0_902:
	s_or_b64 exec, exec, s[64:65]
	v_pk_mul_f32 v[72:73], v[72:73], v[196:197] op_sel_hi:[1,0]
	v_pk_mul_f32 v[98:99], v[68:69], v[196:197] op_sel_hi:[1,0]
	v_pk_mul_f32 v[96:97], v[70:71], v[196:197] op_sel_hi:[1,0]
	v_mov_b32_dpp v68, v72 row_ror:1 row_mask:0xf bank_mask:0xf
	v_mov_b32_dpp v69, v72 row_ror:2 row_mask:0xf bank_mask:0xf
	v_cndmask_b32_e64 v68, v68, v94, s[8:9]
	v_mov_b32_dpp v70, v73 row_ror:1 row_mask:0xf bank_mask:0xf
	v_cndmask_b32_e64 v69, v95, v69, s[10:11]
	v_fma_f32 v72, v148, v72, v152
	v_pk_mul_f32 v[74:75], v[74:75], v[196:197] op_sel_hi:[1,0]
	v_fma_f32 v68, v144, v68, v72
	v_mov_b32_dpp v71, v73 row_ror:2 row_mask:0xf bank_mask:0xf
	v_fma_f32 v68, v136, v69, v68
	v_cndmask_b32_e64 v69, v70, v92, s[8:9]
	v_cndmask_b32_e64 v70, v93, v71, s[10:11]
	v_mov_b32_dpp v100, v74 row_ror:1 row_mask:0xf bank_mask:0xf
	v_fma_f32 v71, v149, v73, v153
	v_fma_f32 v69, v145, v69, v71
	v_fma_f32 v70, v137, v70, v69
	v_cndmask_b32_e64 v69, v100, v90, s[8:9]
	v_mov_b32_dpp v101, v74 row_ror:2 row_mask:0xf bank_mask:0xf
	v_mov_b32_dpp v102, v75 row_ror:1 row_mask:0xf bank_mask:0xf
	v_fma_f32 v72, v150, v74, v154
	v_fma_f32 v69, v146, v69, v72
	v_cndmask_b32_e64 v71, v91, v101, s[10:11]
	v_fma_f32 v72, v138, v71, v69
	v_cndmask_b32_e64 v69, v102, v87, s[8:9]
	v_mov_b32_dpp v103, v75 row_ror:2 row_mask:0xf bank_mask:0xf
	v_mov_b32_dpp v160, v98 row_ror:1 row_mask:0xf bank_mask:0xf
	v_fma_f32 v73, v151, v75, v155
	v_fma_f32 v69, v147, v69, v73
	v_cndmask_b32_e64 v71, v89, v103, s[10:11]
	v_mov_b32_dpp v161, v98 row_ror:2 row_mask:0xf bank_mask:0xf
	v_fma_f32 v73, v139, v71, v69
	v_cndmask_b32_e64 v69, v160, v86, s[8:9]
	v_mov_b32_dpp v162, v99 row_ror:1 row_mask:0xf bank_mask:0xf
	v_cndmask_b32_e64 v71, v88, v161, s[10:11]
	v_fma_f32 v74, v128, v98, v132
	v_fma_f32 v69, v124, v69, v74
	v_mov_b32_dpp v163, v99 row_ror:2 row_mask:0xf bank_mask:0xf
	v_fma_f32 v69, v120, v71, v69
	v_cndmask_b32_e64 v71, v162, v84, s[8:9]
	v_mov_b32_dpp v164, v96 row_ror:1 row_mask:0xf bank_mask:0xf
	v_cndmask_b32_e64 v74, v85, v163, s[10:11]
	v_fma_f32 v75, v129, v99, v133
	v_fma_f32 v71, v125, v71, v75
	v_mov_b32_dpp v165, v96 row_ror:2 row_mask:0xf bank_mask:0xf
	v_fma_f32 v71, v121, v74, v71
	v_cndmask_b32_e64 v74, v164, v82, s[8:9]
	v_mov_b32_dpp v166, v97 row_ror:1 row_mask:0xf bank_mask:0xf
	v_cndmask_b32_e64 v75, v83, v165, s[10:11]
	v_fma_f32 v82, v130, v96, v134
	s_nop 0
	v_fma_f32 v74, v126, v74, v82
	v_mov_b32_dpp v167, v97 row_ror:2 row_mask:0xf bank_mask:0xf
	v_fma_f32 v74, v122, v75, v74
	v_cndmask_b32_e64 v75, v166, v80, s[8:9]
	v_cndmask_b32_e64 v80, v81, v167, s[10:11]
	v_fma_f32 v81, v131, v97, v135
	s_nop 0
	v_fma_f32 v75, v127, v75, v81
	s_nop 0
	v_fma_f32 v75, v123, v80, v75
	v_add_u32_e32 v80, s71, v214
	v_cmp_gt_i32_e32 vcc, s68, v80
	s_and_b64 s[64:65], s[52:53], vcc
	v_add_u32_e32 v227, s59, v80
	s_and_saveexec_b64 s[76:77], s[64:65]
	s_cbranch_execz .LBB0_904
	v_mul_f32_e32 v80, 0xbfb8aa3b, v73
	v_exp_f32_e32 v80, v80
	s_nop 0
	v_add_f32_e32 v80, 1.0, v80
	v_rcp_f32_e32 v80, v80
	s_nop 0
	v_mul_f32_e32 v73, v73, v80
	v_mul_f32_e32 v73, v73, v75
	v_mul_f32_e32 v75, 0xbfb8aa3b, v72
	v_exp_f32_e32 v75, v75
	s_nop 0
	v_add_f32_e32 v75, 1.0, v75
	v_rcp_f32_e32 v75, v75
	s_nop 0
	v_mul_f32_e32 v72, v72, v75
	v_mul_f32_e32 v72, v72, v74
	v_mul_f32_e32 v74, 0xbfb8aa3b, v70
	v_exp_f32_e32 v74, v74
	s_nop 0
	v_add_f32_e32 v74, 1.0, v74
	v_rcp_f32_e32 v74, v74
	s_nop 0
	v_mul_f32_e32 v70, v70, v74
	v_mul_f32_e32 v70, v70, v71
	v_mul_f32_e32 v71, 0xbfb8aa3b, v68
	v_exp_f32_e32 v71, v71
	s_nop 0
	v_add_f32_e32 v71, 1.0, v71
	v_rcp_f32_e32 v71, v71
	s_nop 0
	v_mul_f32_e32 v68, v68, v71
	v_mul_f32_e32 v68, v68, v69
	v_cvt_pk_bf16_f32 v68, v68, v70
	v_mov_b64_e32 v[70:71], s[36:37]
	v_mad_i64_i32 v[70:71], s[72:73], v227, s69, v[70:71]
	v_lshl_add_u64 v[70:71], v[192:193], 1, v[70:71]
	v_cvt_pk_bf16_f32 v69, v72, v73
	global_store_dwordx2 v[70:71], v[68:69], off

; #define PG8_LAS __attribute__((address_space(3)))
; __device__ __forceinline__ float sigmoid_f(float x) { return __builtin_amdgcn_rcpf(1.0f + __builtin_amdgcn_exp2f(-1.4426950408889634f * x)); }
;     __device__ __forceinline__ void operator()(const f32x4 (&acc)[2][2][4][2], const Unit& u, int wr, int wc, int fr, int fq) const {
;     ...
;             for (int ai = 0; ai < 2; ++ai) {
;                 f32x4 pr1[2] = {zero4, zero4}, pr2[2] = {zero4, zero4};
;                 const bool hasprev = (wr == 1) || (ai == 1);
;                 const int pg = (wr == 1) ? ai * 2 : (ai - 1) * 2 + 1;
;                 if (hasprev && fr < 2) {
; #pragma unroll
;                     for (int bj = 0; bj < 2; ++bj) {
;                         pr2[bj] = *(const PG8_LAS f32x4*)(xch + ((pg * 2 + fr) * 256 + bj * 128 + colx + n * 4));
;                         pr1[bj] = *(const PG8_LAS f32x4*)(xch + ((pg * 2 + 1) * 256 + bj * 128 + colx + n * 4)); }
;                 }
; #pragma unroll
;                 for (int m = 0; m < 4; ++m) {
;                     f32x4 cur[2] = {acc[ai][0][m][n] * r2v[ai][m], acc[ai][1][m][n] * r2v[ai][m]};
;                     if (first && ai == 0 && wr == 0 && m == 0 && fr < 2) { cur[0] = zero4; cur[1] = zero4; }
;                     f32x4 r1[2], r2[2], av[2];
; #pragma unroll
;                     for (int bj = 0; bj < 2; ++bj)
; #pragma unroll
;                         for (int e = 0; e < 4; ++e) { r1[bj][e] = dpp_ror1(cur[bj][e]); r2[bj][e] = dpp_ror2(cur[bj][e]); }
; #pragma unroll
;                     for (int bj = 0; bj < 2; ++bj)
; #pragma unroll
;                         for (int e = 0; e < 4; ++e) { const float p1 = fr >= 1 ? r1[bj][e] : pr1[bj][e], p2 = fr >= 2 ? r2[bj][e] : pr2[bj][e];
;                             av[bj][e] = fma_s(w0[bj][e], p2, fma_s(w1[bj][e], p1, fma_s(w2[bj][e], cur[bj][e], bb[bj][e]))); }
;                     float o[4];
; #pragma unroll
;                     for (int e = 0; e < 4; ++e) o[e] = av[0][e] * sigmoid_f(av[0][e]) * av[1][e];
;                     const int lr = ai * HALF + wr * 64 + m * 16 + fr, t = t0 + lr;
;                     if (lr >= 2 && t < 4096) { u32x2 w; w.x = cvt_pk_bf16(o[0], o[1]); w.y = cvt_pk_bf16(o[2], o[3]);
;                         *(u32x2*)(gout + (size_t)(b * 4096 + t) * FF + j0 + n * 4) = w; }
;                     pr1[0] = r1[0]; pr1[1] = r1[1]; pr2[0] = r2[0]; pr2[1] = r2[1];
.LBB0_906:
	s_or_b64 exec, exec, s[76:77]
	v_fmamk_f32 v202, v229, 0x3a000000, v224
	v_mul_f32_e32 v203, 0x4b800000, v202
	v_cmp_gt_f32_e32 vcc, s35, v202
	s_nop 1
	v_cndmask_b32_e32 v202, v202, v203, vcc
	v_rsq_f32_e32 v202, v202
	s_nop 0
	v_mul_f32_e32 v203, 0x45800000, v202
	v_cndmask_b32_e32 v202, v202, v203, vcc
	v_pk_mul_f32 v[238:239], v[156:157], v[202:203] op_sel_hi:[1,0]
	v_pk_mul_f32 v[242:243], v[140:141], v[202:203] op_sel_hi:[1,0]
	v_pk_mul_f32 v[236:237], v[158:159], v[202:203] op_sel_hi:[1,0]
	v_mov_b32_dpp v234, v238 row_ror:1 row_mask:0xf bank_mask:0xf
	v_mov_b32_dpp v235, v238 row_ror:2 row_mask:0xf bank_mask:0xf
	s_waitcnt lgkmcnt(1)
	v_cndmask_b32_e64 v140, v234, v168, s[8:9]
	v_mov_b32_dpp v232, v239 row_ror:1 row_mask:0xf bank_mask:0xf
	v_cndmask_b32_e64 v141, v172, v235, s[10:11]
	v_fma_f32 v168, v148, v238, v152
	v_mov_b32_dpp v233, v239 row_ror:2 row_mask:0xf bank_mask:0xf
	v_fma_f32 v140, v144, v140, v168
	v_mov_b32_dpp v230, v236 row_ror:1 row_mask:0xf bank_mask:0xf
	v_fma_f32 v140, v136, v141, v140
	v_cndmask_b32_e64 v141, v232, v169, s[8:9]
	v_cndmask_b32_e64 v168, v173, v233, s[10:11]
	v_fma_f32 v169, v149, v239, v153
	v_fma_f32 v141, v145, v141, v169
	v_mov_b32_dpp v231, v236 row_ror:2 row_mask:0xf bank_mask:0xf
	v_fma_f32 v168, v137, v168, v141
	v_cndmask_b32_e64 v141, v230, v170, s[8:9]
	v_mov_b32_dpp v206, v237 row_ror:1 row_mask:0xf bank_mask:0xf
	v_cndmask_b32_e64 v169, v174, v231, s[10:11]
	v_fma_f32 v170, v150, v236, v154
	v_pk_mul_f32 v[240:241], v[142:143], v[202:203] op_sel_hi:[1,0]
	v_fma_f32 v141, v146, v141, v170
	v_mov_b32_dpp v229, v237 row_ror:2 row_mask:0xf bank_mask:0xf
	v_fma_f32 v169, v138, v169, v141
	v_cndmask_b32_e64 v141, v206, v171, s[8:9]
	v_mov_b32_dpp v203, v242 row_ror:1 row_mask:0xf bank_mask:0xf
	v_cndmask_b32_e64 v170, v175, v229, s[10:11]
	v_fma_f32 v171, v151, v237, v155
	v_mov_b32_dpp v207, v242 row_ror:2 row_mask:0xf bank_mask:0xf
	v_fma_f32 v141, v147, v141, v171
	v_fma_f32 v170, v139, v170, v141
	s_waitcnt lgkmcnt(0)
	v_cndmask_b32_e64 v141, v203, v160, s[8:9]
	v_mov_b32_dpp v158, v243 row_ror:1 row_mask:0xf bank_mask:0xf
	v_cndmask_b32_e64 v160, v164, v207, s[10:11]
	v_fma_f32 v164, v128, v242, v132
	v_mov_b32_dpp v159, v243 row_ror:2 row_mask:0xf bank_mask:0xf
	v_fma_f32 v141, v124, v141, v164
	v_fma_f32 v160, v120, v160, v141
	v_cndmask_b32_e64 v141, v158, v161, s[8:9]
	v_mov_b32_dpp v156, v240 row_ror:1 row_mask:0xf bank_mask:0xf
	v_cndmask_b32_e64 v161, v165, v159, s[10:11]
	v_fma_f32 v164, v129, v243, v133
	v_mov_b32_dpp v157, v240 row_ror:2 row_mask:0xf bank_mask:0xf
	v_fma_f32 v141, v125, v141, v164
	v_fma_f32 v161, v121, v161, v141
	v_cndmask_b32_e64 v141, v156, v162, s[8:9]
	v_mov_b32_dpp v142, v241 row_ror:1 row_mask:0xf bank_mask:0xf
	v_cndmask_b32_e64 v162, v166, v157, s[10:11]
	v_fma_f32 v164, v130, v240, v134
	v_mov_b32_dpp v143, v241 row_ror:2 row_mask:0xf bank_mask:0xf
	v_fma_f32 v141, v126, v141, v164
	v_fma_f32 v164, v131, v241, v135
	s_nop 0
	v_fma_f32 v162, v122, v162, v141
	v_cndmask_b32_e64 v141, v142, v163, s[8:9]
	v_cndmask_b32_e64 v163, v167, v143, s[10:11]
	v_fma_f32 v141, v127, v141, v164
	s_nop 0
	v_fma_f32 v163, v123, v163, v141
	v_add_u32_e32 v141, 0x80, v201
	v_cmp_gt_i32_e32 vcc, s68, v141
	s_and_b64 s[76:77], s[4:5], vcc
	v_add_u32_e32 v141, s59, v141
	s_and_saveexec_b64 s[82:83], s[76:77]
	s_cbranch_execz .LBB0_908
	v_mul_f32_e32 v164, 0xbfb8aa3b, v170
	v_exp_f32_e32 v164, v164
	s_nop 0
	v_add_f32_e32 v164, 1.0, v164
	v_rcp_f32_e32 v164, v164
	s_nop 0
	v_mul_f32_e32 v164, v170, v164
	v_mul_f32_e32 v163, v164, v163
	v_mul_f32_e32 v164, 0xbfb8aa3b, v169
	v_exp_f32_e32 v164, v164
	s_nop 0
	v_add_f32_e32 v164, 1.0, v164
	v_rcp_f32_e32 v164, v164
	s_nop 0
	v_mul_f32_e32 v164, v169, v164
	v_mul_f32_e32 v162, v164, v162
	v_mul_f32_e32 v164, 0xbfb8aa3b, v168
	v_exp_f32_e32 v164, v164
	s_nop 0
	v_add_f32_e32 v164, 1.0, v164
	v_rcp_f32_e32 v164, v164
	s_nop 0
	v_mul_f32_e32 v164, v168, v164
	v_mul_f32_e32 v161, v164, v161
	v_mul_f32_e32 v164, 0xbfb8aa3b, v140
	v_exp_f32_e32 v164, v164
	s_nop 0
	v_add_f32_e32 v164, 1.0, v164
	v_rcp_f32_e32 v164, v164
	s_nop 0
	v_mul_f32_e32 v140, v140, v164
	v_mul_f32_e32 v140, v140, v160
	v_cvt_pk_bf16_f32 v160, v140, v161
	v_cvt_pk_bf16_f32 v161, v162, v163
	v_mov_b64_e32 v[162:163], s[36:37]
	v_mad_i64_i32 v[162:163], s[72:73], v141, s69, v[162:163]
	v_lshl_add_u64 v[162:163], v[192:193], 1, v[162:163]
	global_store_dwordx2 v[162:163], v[160:161], off
; __device__ __forceinline__ unsigned cvt_pk_bf16(float lo, float hi) { unsigned r; asm volatile("v_cvt_pk_bf16_f32 %0, %1, %2" : "=v"(r) : "v"(lo), "v"(hi)); return r; }
; __device__ __forceinline__ float sigmoid_f(float x) { return __builtin_amdgcn_rcpf(1.0f + __builtin_amdgcn_exp2f(-1.4426950408889634f * x)); }
; __device__ __forceinline__ float dpp_ror1(float v) { return __builtin_bit_cast(float, __builtin_amdgcn_update_dpp(0, __builtin_bit_cast(int, v), 0x121, 0xf, 0xf, false)); }
; __device__ __forceinline__ float dpp_ror2(float v) { return __builtin_bit_cast(float, __builtin_amdgcn_update_dpp(0, __builtin_bit_cast(int, v), 0x122, 0xf, 0xf, false)); }
; __device__ __forceinline__ float fma_s(float a, float b, float c) { float r; asm("v_fma_f32 %0, %1, %2, %3" : "=v"(r) : "v"(a), "v"(b), "v"(c)); return r; }
;     __device__ __forceinline__ void operator()(const f32x4 (&acc)[2][2][4][2], const Unit& u, int wr, int wc, int fr, int fq) const {
;     ...
;                 for (int m = 0; m < 4; ++m) {
;                     f32x4 cur[2] = {acc[ai][0][m][n] * r2v[ai][m], acc[ai][1][m][n] * r2v[ai][m]};
;                     if (first && ai == 0 && wr == 0 && m == 0 && fr < 2) { cur[0] = zero4; cur[1] = zero4; }
;                     f32x4 r1[2], r2[2], av[2];
; #pragma unroll
;                     for (int bj = 0; bj < 2; ++bj)
; #pragma unroll
;                         for (int e = 0; e < 4; ++e) { r1[bj][e] = dpp_ror1(cur[bj][e]); r2[bj][e] = dpp_ror2(cur[bj][e]); }
; #pragma unroll
;                     for (int bj = 0; bj < 2; ++bj)
; #pragma unroll
;                         for (int e = 0; e < 4; ++e) { const float p1 = fr >= 1 ? r1[bj][e] : pr1[bj][e], p2 = fr >= 2 ? r2[bj][e] : pr2[bj][e];
;                             av[bj][e] = fma_s(w0[bj][e], p2, fma_s(w1[bj][e], p1, fma_s(w2[bj][e], cur[bj][e], bb[bj][e]))); }
;                     float o[4];
; #pragma unroll
;                     for (int e = 0; e < 4; ++e) o[e] = av[0][e] * sigmoid_f(av[0][e]) * av[1][e];
;                     const int lr = ai * HALF + wr * 64 + m * 16 + fr, t = t0 + lr;
;                     if (lr >= 2 && t < 4096) { u32x2 w; w.x = cvt_pk_bf16(o[0], o[1]); w.y = cvt_pk_bf16(o[2], o[3]);
;                         *(u32x2*)(gout + (size_t)(b * 4096 + t) * FF + j0 + n * 4) = w; }
;                     pr1[0] = r1[0]; pr1[1] = r1[1]; pr2[0] = r2[0]; pr2[1] = r2[1];
.LBB0_908:
	s_or_b64 exec, exec, s[82:83]
	v_fmamk_f32 v140, v228, 0x3a000000, v224
	v_mul_f32_e32 v160, 0x4b800000, v140
	v_cmp_gt_f32_e32 vcc, s35, v140
	s_nop 1
	v_cndmask_b32_e32 v140, v140, v160, vcc
	v_rsq_f32_e32 v140, v140
	s_nop 0
	v_mul_f32_e32 v160, 0x45800000, v140
	v_cndmask_b32_e32 v140, v140, v160, vcc
	v_pk_mul_f32 v[170:171], v[116:117], v[140:141] op_sel_hi:[1,0]
	v_pk_mul_f32 v[236:237], v[112:113], v[140:141] op_sel_hi:[1,0]
	v_pk_mul_f32 v[172:173], v[118:119], v[140:141] op_sel_hi:[1,0]
	v_mov_b32_dpp v168, v170 row_ror:1 row_mask:0xf bank_mask:0xf
	v_mov_b32_dpp v169, v170 row_ror:2 row_mask:0xf bank_mask:0xf
	v_cndmask_b32_e64 v112, v168, v234, s[8:9]
	v_mov_b32_dpp v166, v171 row_ror:1 row_mask:0xf bank_mask:0xf
	v_cndmask_b32_e64 v113, v235, v169, s[10:11]
	v_fma_f32 v170, v148, v170, v152
	v_mov_b32_dpp v167, v171 row_ror:2 row_mask:0xf bank_mask:0xf
	v_fma_f32 v112, v144, v112, v170
	v_mov_b32_dpp v164, v172 row_ror:1 row_mask:0xf bank_mask:0xf
	v_fma_f32 v112, v136, v113, v112
	v_cndmask_b32_e64 v113, v166, v232, s[8:9]
	v_fma_f32 v171, v149, v171, v153
	v_fma_f32 v113, v145, v113, v171
	v_cndmask_b32_e64 v170, v233, v167, s[10:11]
	v_fma_f32 v171, v137, v170, v113
	v_cndmask_b32_e64 v113, v164, v230, s[8:9]
	v_mov_b32_dpp v165, v172 row_ror:2 row_mask:0xf bank_mask:0xf
	v_mov_b32_dpp v161, v173 row_ror:1 row_mask:0xf bank_mask:0xf
	v_fma_f32 v172, v150, v172, v154
	v_fma_f32 v113, v146, v113, v172
	v_cndmask_b32_e64 v170, v231, v165, s[10:11]
	v_fma_f32 v172, v138, v170, v113
	v_cndmask_b32_e64 v113, v161, v206, s[8:9]
	v_mov_b32_dpp v163, v173 row_ror:2 row_mask:0xf bank_mask:0xf
	v_mov_b32_dpp v160, v236 row_ror:1 row_mask:0xf bank_mask:0xf
	v_fma_f32 v173, v151, v173, v155
	v_fma_f32 v113, v147, v113, v173
	v_cndmask_b32_e64 v170, v229, v163, s[10:11]
	v_mov_b32_dpp v162, v236 row_ror:2 row_mask:0xf bank_mask:0xf
	v_fma_f32 v173, v139, v170, v113
	v_cndmask_b32_e64 v113, v160, v203, s[8:9]
	v_mov_b32_dpp v118, v237 row_ror:1 row_mask:0xf bank_mask:0xf
	v_cndmask_b32_e64 v170, v207, v162, s[10:11]
	v_fma_f32 v203, v128, v236, v132
	v_pk_mul_f32 v[174:175], v[114:115], v[140:141] op_sel_hi:[1,0]
	v_fma_f32 v113, v124, v113, v203
	v_mov_b32_dpp v119, v237 row_ror:2 row_mask:0xf bank_mask:0xf
	v_fma_f32 v170, v120, v170, v113
	v_cndmask_b32_e64 v113, v118, v158, s[8:9]
	v_mov_b32_dpp v116, v174 row_ror:1 row_mask:0xf bank_mask:0xf
	v_cndmask_b32_e64 v158, v159, v119, s[10:11]
	v_fma_f32 v159, v129, v237, v133
	v_mov_b32_dpp v117, v174 row_ror:2 row_mask:0xf bank_mask:0xf
	v_fma_f32 v113, v125, v113, v159
	v_fma_f32 v158, v121, v158, v113
	v_cndmask_b32_e64 v113, v116, v156, s[8:9]
	v_mov_b32_dpp v114, v175 row_ror:1 row_mask:0xf bank_mask:0xf
	v_cndmask_b32_e64 v156, v157, v117, s[10:11]
	v_fma_f32 v157, v130, v174, v134
	v_mov_b32_dpp v115, v175 row_ror:2 row_mask:0xf bank_mask:0xf
	v_fma_f32 v113, v126, v113, v157
	v_readlane_b32 s12, v254, 22
	v_fma_f32 v156, v122, v156, v113
	v_cndmask_b32_e64 v113, v114, v142, s[8:9]
	v_cndmask_b32_e64 v142, v143, v115, s[10:11]
	v_fma_f32 v143, v131, v175, v135
	v_readlane_b32 s13, v254, 23
	v_fma_f32 v113, v127, v113, v143
	s_nop 0
	v_fma_f32 v142, v123, v142, v113
	v_add_u32_e32 v113, 0x90, v201
	v_cmp_gt_i32_e32 vcc, s68, v113
	s_and_b64 s[82:83], s[12:13], vcc
	v_add_u32_e32 v113, s59, v113
	s_and_saveexec_b64 s[84:85], s[82:83]
	s_cbranch_execz .LBB0_910
	v_mul_f32_e32 v143, 0xbfb8aa3b, v173
	v_exp_f32_e32 v143, v143
	v_mul_f32_e32 v157, 0xbfb8aa3b, v112
	v_exp_f32_e32 v157, v157
	v_add_f32_e32 v143, 1.0, v143
	v_rcp_f32_e32 v143, v143
	v_add_f32_e32 v157, 1.0, v157
	v_rcp_f32_e32 v157, v157
	v_mul_f32_e32 v143, v173, v143
	v_mul_f32_e32 v143, v143, v142
	v_mul_f32_e32 v142, 0xbfb8aa3b, v172
	v_exp_f32_e32 v142, v142
	v_mul_f32_e32 v112, v112, v157
	v_mul_f32_e32 v112, v112, v170
	v_add_f32_e32 v142, 1.0, v142
	v_rcp_f32_e32 v142, v142
	s_nop 0
	v_mul_f32_e32 v142, v172, v142
	v_mul_f32_e32 v156, v142, v156
	v_mul_f32_e32 v142, 0xbfb8aa3b, v171
	v_exp_f32_e32 v142, v142
	s_nop 0
	v_add_f32_e32 v142, 1.0, v142
	v_rcp_f32_e32 v142, v142
	s_nop 0
	v_mul_f32_e32 v142, v171, v142
	v_mul_f32_e32 v142, v142, v158
	v_cvt_pk_bf16_f32 v142, v112, v142
	v_cvt_pk_bf16_f32 v143, v156, v143
	v_mov_b64_e32 v[156:157], s[36:37]
	v_mad_i64_i32 v[156:157], s[72:73], v113, s69, v[156:157]
	v_lshl_add_u64 v[156:157], v[192:193], 1, v[156:157]
	global_store_dwordx2 v[156:157], v[142:143], off
; __device__ __forceinline__ unsigned cvt_pk_bf16(float lo, float hi) { unsigned r; asm volatile("v_cvt_pk_bf16_f32 %0, %1, %2" : "=v"(r) : "v"(lo), "v"(hi)); return r; }
; __device__ __forceinline__ float sigmoid_f(float x) { return __builtin_amdgcn_rcpf(1.0f + __builtin_amdgcn_exp2f(-1.4426950408889634f * x)); }
; __device__ __forceinline__ float dpp_ror1(float v) { return __builtin_bit_cast(float, __builtin_amdgcn_update_dpp(0, __builtin_bit_cast(int, v), 0x121, 0xf, 0xf, false)); }
; __device__ __forceinline__ float dpp_ror2(float v) { return __builtin_bit_cast(float, __builtin_amdgcn_update_dpp(0, __builtin_bit_cast(int, v), 0x122, 0xf, 0xf, false)); }
; __device__ __forceinline__ float fma_s(float a, float b, float c) { float r; asm("v_fma_f32 %0, %1, %2, %3" : "=v"(r) : "v"(a), "v"(b), "v"(c)); return r; }
;     __device__ __forceinline__ void operator()(const f32x4 (&acc)[2][2][4][2], const Unit& u, int wr, int wc, int fr, int fq) const {
;     ...
;                 for (int m = 0; m < 4; ++m) {
;                     f32x4 cur[2] = {acc[ai][0][m][n] * r2v[ai][m], acc[ai][1][m][n] * r2v[ai][m]};
;                     if (first && ai == 0 && wr == 0 && m == 0 && fr < 2) { cur[0] = zero4; cur[1] = zero4; }
;                     f32x4 r1[2], r2[2], av[2];
; #pragma unroll
;                     for (int bj = 0; bj < 2; ++bj)
; #pragma unroll
;                         for (int e = 0; e < 4; ++e) { r1[bj][e] = dpp_ror1(cur[bj][e]); r2[bj][e] = dpp_ror2(cur[bj][e]); }
; #pragma unroll
;                     for (int bj = 0; bj < 2; ++bj)
; #pragma unroll
;                         for (int e = 0; e < 4; ++e) { const float p1 = fr >= 1 ? r1[bj][e] : pr1[bj][e], p2 = fr >= 2 ? r2[bj][e] : pr2[bj][e];
;                             av[bj][e] = fma_s(w0[bj][e], p2, fma_s(w1[bj][e], p1, fma_s(w2[bj][e], cur[bj][e], bb[bj][e]))); }
;                     float o[4];
; #pragma unroll
;                     for (int e = 0; e < 4; ++e) o[e] = av[0][e] * sigmoid_f(av[0][e]) * av[1][e];
;                     const int lr = ai * HALF + wr * 64 + m * 16 + fr, t = t0 + lr;
;                     if (lr >= 2 && t < 4096) { u32x2 w; w.x = cvt_pk_bf16(o[0], o[1]); w.y = cvt_pk_bf16(o[2], o[3]);
;                         *(u32x2*)(gout + (size_t)(b * 4096 + t) * FF + j0 + n * 4) = w; }
;                     pr1[0] = r1[0]; pr1[1] = r1[1]; pr2[0] = r2[0]; pr2[1] = r2[1];
.LBB0_910:
	s_or_b64 exec, exec, s[84:85]
	v_fmamk_f32 v112, v205, 0x3a000000, v224
	v_mul_f32_e32 v142, 0x4b800000, v112
	v_cmp_gt_f32_e32 vcc, s35, v112
	s_nop 1
	v_cndmask_b32_e32 v112, v112, v142, vcc
	v_rsq_f32_e32 v112, v112
	s_nop 0
	v_mul_f32_e32 v142, 0x45800000, v112
	v_cndmask_b32_e32 v112, v112, v142, vcc
	v_pk_mul_f32 v[174:175], v[108:109], v[112:113] op_sel_hi:[1,0]
	v_pk_mul_f32 v[172:173], v[110:111], v[112:113] op_sel_hi:[1,0]
	s_nop 0
	v_mov_b32_dpp v170, v174 row_ror:1 row_mask:0xf bank_mask:0xf
	v_mov_b32_dpp v171, v174 row_ror:2 row_mask:0xf bank_mask:0xf
	v_mov_b32_dpp v158, v175 row_ror:1 row_mask:0xf bank_mask:0xf
	v_cndmask_b32_e64 v168, v170, v168, s[8:9]
	v_mov_b32_dpp v159, v175 row_ror:2 row_mask:0xf bank_mask:0xf
	v_mov_b32_dpp v156, v172 row_ror:1 row_mask:0xf bank_mask:0xf
	v_cndmask_b32_e64 v169, v169, v171, s[10:11]
	v_fma_f32 v174, v148, v174, v152
	v_cndmask_b32_e64 v166, v158, v166, s[8:9]
	v_fma_f32 v168, v144, v168, v174
	v_pk_mul_f32 v[228:229], v[104:105], v[112:113] op_sel_hi:[1,0]
	v_mov_b32_dpp v157, v172 row_ror:2 row_mask:0xf bank_mask:0xf
	v_mov_b32_dpp v111, v173 row_ror:1 row_mask:0xf bank_mask:0xf
	v_fma_f32 v168, v136, v169, v168
	v_cndmask_b32_e64 v167, v167, v159, s[10:11]
	v_fma_f32 v169, v149, v175, v153
	v_cndmask_b32_e64 v164, v156, v164, s[8:9]
	v_fma_f32 v166, v145, v166, v169
	v_mov_b32_dpp v143, v173 row_ror:2 row_mask:0xf bank_mask:0xf
	v_mov_b32_dpp v110, v228 row_ror:1 row_mask:0xf bank_mask:0xf
	v_fma_f32 v166, v137, v167, v166
	v_cndmask_b32_e64 v165, v165, v157, s[10:11]
	v_fma_f32 v167, v150, v172, v154
	v_cndmask_b32_e64 v161, v111, v161, s[8:9]
	v_fma_f32 v164, v146, v164, v167
	v_pk_mul_f32 v[206:207], v[106:107], v[112:113] op_sel_hi:[1,0]
	v_mov_b32_dpp v142, v228 row_ror:2 row_mask:0xf bank_mask:0xf
	v_mov_b32_dpp v108, v229 row_ror:1 row_mask:0xf bank_mask:0xf
	v_fma_f32 v164, v138, v165, v164
	v_cndmask_b32_e64 v163, v163, v143, s[10:11]
	v_fma_f32 v165, v151, v173, v155
	v_cndmask_b32_e64 v160, v110, v160, s[8:9]
	v_fma_f32 v161, v147, v161, v165
	v_mov_b32_dpp v109, v229 row_ror:2 row_mask:0xf bank_mask:0xf
	v_mov_b32_dpp v106, v206 row_ror:1 row_mask:0xf bank_mask:0xf
	v_fma_f32 v161, v139, v163, v161
	v_cndmask_b32_e64 v162, v162, v142, s[10:11]
	v_fma_f32 v163, v128, v228, v132
	v_cndmask_b32_e64 v118, v108, v118, s[8:9]
	v_fma_f32 v160, v124, v160, v163
	v_mov_b32_dpp v107, v206 row_ror:2 row_mask:0xf bank_mask:0xf
	v_mov_b32_dpp v104, v207 row_ror:1 row_mask:0xf bank_mask:0xf
	v_fma_f32 v160, v120, v162, v160
	v_cndmask_b32_e64 v119, v119, v109, s[10:11]
	v_fma_f32 v162, v129, v229, v133
	v_cndmask_b32_e64 v116, v106, v116, s[8:9]
	v_fma_f32 v118, v125, v118, v162
	v_mov_b32_dpp v105, v207 row_ror:2 row_mask:0xf bank_mask:0xf
	v_fma_f32 v118, v121, v119, v118
	v_cndmask_b32_e64 v117, v117, v107, s[10:11]
	v_fma_f32 v119, v130, v206, v134
	v_cndmask_b32_e64 v114, v104, v114, s[8:9]
	v_fma_f32 v116, v126, v116, v119
	v_cndmask_b32_e64 v115, v115, v105, s[10:11]
	v_fma_f32 v116, v122, v117, v116
	v_fma_f32 v117, v131, v207, v135
	v_readlane_b32 s12, v254, 24
	v_fma_f32 v114, v127, v114, v117
	v_readlane_b32 s13, v254, 25
	v_fma_f32 v115, v123, v115, v114
	v_add_u32_e32 v114, 0xa0, v201
	v_cmp_gt_i32_e32 vcc, s68, v114
	s_and_b64 s[84:85], s[12:13], vcc
	v_add_u32_e32 v114, s59, v114
	s_and_saveexec_b64 s[86:87], s[84:85]
	s_cbranch_execz .LBB0_912
	v_mul_f32_e32 v117, 0xbfb8aa3b, v161
	v_exp_f32_e32 v117, v117
	s_nop 0
	v_add_f32_e32 v117, 1.0, v117
	v_rcp_f32_e32 v117, v117
	s_nop 0
	v_mul_f32_e32 v117, v161, v117
	v_mul_f32_e32 v115, v117, v115
	v_mul_f32_e32 v117, 0xbfb8aa3b, v164
	v_exp_f32_e32 v117, v117
	s_nop 0
	v_add_f32_e32 v117, 1.0, v117
	v_rcp_f32_e32 v117, v117
	s_nop 0
	v_mul_f32_e32 v117, v164, v117
	v_mul_f32_e32 v117, v117, v116
	v_mul_f32_e32 v116, 0xbfb8aa3b, v166
	v_exp_f32_e32 v116, v116
	s_nop 0
	v_add_f32_e32 v116, 1.0, v116
	v_rcp_f32_e32 v116, v116
	s_nop 0
	v_mul_f32_e32 v116, v166, v116
	v_mul_f32_e32 v116, v116, v118
	v_mul_f32_e32 v118, 0xbfb8aa3b, v168
	v_exp_f32_e32 v118, v118
	s_nop 0
	v_add_f32_e32 v118, 1.0, v118
	v_rcp_f32_e32 v118, v118
	s_nop 0
	v_mul_f32_e32 v118, v168, v118
	v_mul_f32_e32 v118, v118, v160
	v_cvt_pk_bf16_f32 v116, v118, v116
	v_mov_b64_e32 v[118:119], s[36:37]
	v_mad_i64_i32 v[118:119], s[72:73], v114, s69, v[118:119]
	v_lshl_add_u64 v[118:119], v[192:193], 1, v[118:119]
	v_cvt_pk_bf16_f32 v117, v117, v115
	global_store_dwordx2 v[118:119], v[116:117], off
; __device__ __forceinline__ unsigned cvt_pk_bf16(float lo, float hi) { unsigned r; asm volatile("v_cvt_pk_bf16_f32 %0, %1, %2" : "=v"(r) : "v"(lo), "v"(hi)); return r; }
; __device__ __forceinline__ float sigmoid_f(float x) { return __builtin_amdgcn_rcpf(1.0f + __builtin_amdgcn_exp2f(-1.4426950408889634f * x)); }
; __device__ __forceinline__ float dpp_ror1(float v) { return __builtin_bit_cast(float, __builtin_amdgcn_update_dpp(0, __builtin_bit_cast(int, v), 0x121, 0xf, 0xf, false)); }
; __device__ __forceinline__ float dpp_ror2(float v) { return __builtin_bit_cast(float, __builtin_amdgcn_update_dpp(0, __builtin_bit_cast(int, v), 0x122, 0xf, 0xf, false)); }
; __device__ __forceinline__ float fma_s(float a, float b, float c) { float r; asm("v_fma_f32 %0, %1, %2, %3" : "=v"(r) : "v"(a), "v"(b), "v"(c)); return r; }
;     __device__ __forceinline__ void operator()(const f32x4 (&acc)[2][2][4][2], const Unit& u, int wr, int wc, int fr, int fq) const {
;     ...
;                 for (int m = 0; m < 4; ++m) {
;                     f32x4 cur[2] = {acc[ai][0][m][n] * r2v[ai][m], acc[ai][1][m][n] * r2v[ai][m]};
;                     if (first && ai == 0 && wr == 0 && m == 0 && fr < 2) { cur[0] = zero4; cur[1] = zero4; }
;                     f32x4 r1[2], r2[2], av[2];
; #pragma unroll
;                     for (int bj = 0; bj < 2; ++bj)
; #pragma unroll
;                         for (int e = 0; e < 4; ++e) { r1[bj][e] = dpp_ror1(cur[bj][e]); r2[bj][e] = dpp_ror2(cur[bj][e]); }
; #pragma unroll
;                     for (int bj = 0; bj < 2; ++bj)
; #pragma unroll
;                         for (int e = 0; e < 4; ++e) { const float p1 = fr >= 1 ? r1[bj][e] : pr1[bj][e], p2 = fr >= 2 ? r2[bj][e] : pr2[bj][e];
;                             av[bj][e] = fma_s(w0[bj][e], p2, fma_s(w1[bj][e], p1, fma_s(w2[bj][e], cur[bj][e], bb[bj][e]))); }
;                     float o[4];
; #pragma unroll
;                     for (int e = 0; e < 4; ++e) o[e] = av[0][e] * sigmoid_f(av[0][e]) * av[1][e];
;                     const int lr = ai * HALF + wr * 64 + m * 16 + fr, t = t0 + lr;
;                     if (lr >= 2 && t < 4096) { u32x2 w; w.x = cvt_pk_bf16(o[0], o[1]); w.y = cvt_pk_bf16(o[2], o[3]);
;                         *(u32x2*)(gout + (size_t)(b * 4096 + t) * FF + j0 + n * 4) = w; }
;                     pr1[0] = r1[0]; pr1[1] = r1[1]; pr2[0] = r2[0]; pr2[1] = r2[1];
.LBB0_912:
	s_or_b64 exec, exec, s[86:87]
	v_pk_mul_f32 v[76:77], v[76:77], v[194:195] op_sel_hi:[1,0]
	v_pk_mul_f32 v[118:119], v[64:65], v[194:195] op_sel_hi:[1,0]
	v_pk_mul_f32 v[116:117], v[66:67], v[194:195] op_sel_hi:[1,0]
	v_mov_b32_dpp v64, v76 row_ror:1 row_mask:0xf bank_mask:0xf
	v_mov_b32_dpp v65, v76 row_ror:2 row_mask:0xf bank_mask:0xf
	v_cndmask_b32_e64 v64, v64, v170, s[8:9]
	v_mov_b32_dpp v66, v77 row_ror:1 row_mask:0xf bank_mask:0xf
	v_cndmask_b32_e64 v65, v171, v65, s[10:11]
	v_fma_f32 v76, v148, v76, v152
	v_pk_mul_f32 v[78:79], v[78:79], v[194:195] op_sel_hi:[1,0]
	v_fma_f32 v64, v144, v64, v76
	v_mov_b32_dpp v67, v77 row_ror:2 row_mask:0xf bank_mask:0xf
	v_fma_f32 v64, v136, v65, v64
	v_cndmask_b32_e64 v65, v66, v158, s[8:9]
	v_cndmask_b32_e64 v66, v159, v67, s[10:11]
	v_mov_b32_dpp v115, v78 row_ror:1 row_mask:0xf bank_mask:0xf
	v_fma_f32 v67, v149, v77, v153
	v_fma_f32 v65, v145, v65, v67
	v_fma_f32 v66, v137, v66, v65
	v_cndmask_b32_e64 v65, v115, v156, s[8:9]
	v_mov_b32_dpp v160, v78 row_ror:2 row_mask:0xf bank_mask:0xf
	v_mov_b32_dpp v161, v79 row_ror:1 row_mask:0xf bank_mask:0xf
	v_fma_f32 v76, v150, v78, v154
	v_fma_f32 v65, v146, v65, v76
	v_cndmask_b32_e64 v67, v157, v160, s[10:11]
	v_fma_f32 v76, v138, v67, v65
	v_cndmask_b32_e64 v65, v161, v111, s[8:9]
	v_mov_b32_dpp v162, v79 row_ror:2 row_mask:0xf bank_mask:0xf
	v_mov_b32_dpp v163, v118 row_ror:1 row_mask:0xf bank_mask:0xf
	v_fma_f32 v77, v151, v79, v155
	v_fma_f32 v65, v147, v65, v77
	v_cndmask_b32_e64 v67, v143, v162, s[10:11]
	v_mov_b32_dpp v164, v118 row_ror:2 row_mask:0xf bank_mask:0xf
	v_fma_f32 v77, v139, v67, v65
	v_cndmask_b32_e64 v65, v163, v110, s[8:9]
	v_mov_b32_dpp v165, v119 row_ror:1 row_mask:0xf bank_mask:0xf
	v_cndmask_b32_e64 v67, v142, v164, s[10:11]
	v_fma_f32 v78, v128, v118, v132
	v_fma_f32 v65, v124, v65, v78
	v_mov_b32_dpp v166, v119 row_ror:2 row_mask:0xf bank_mask:0xf
	v_fma_f32 v65, v120, v67, v65
	v_cndmask_b32_e64 v67, v165, v108, s[8:9]
	v_mov_b32_dpp v167, v116 row_ror:1 row_mask:0xf bank_mask:0xf
	v_cndmask_b32_e64 v78, v109, v166, s[10:11]
	v_fma_f32 v79, v129, v119, v133
	v_fma_f32 v67, v125, v67, v79
	v_mov_b32_dpp v168, v116 row_ror:2 row_mask:0xf bank_mask:0xf
	v_fma_f32 v67, v121, v78, v67
	v_cndmask_b32_e64 v78, v167, v106, s[8:9]
	v_mov_b32_dpp v169, v117 row_ror:1 row_mask:0xf bank_mask:0xf
	v_cndmask_b32_e64 v79, v107, v168, s[10:11]
	v_fma_f32 v106, v130, v116, v134
	s_nop 0
	v_fma_f32 v78, v126, v78, v106
	v_mov_b32_dpp v172, v117 row_ror:2 row_mask:0xf bank_mask:0xf
	v_fma_f32 v78, v122, v79, v78
	v_cndmask_b32_e64 v79, v169, v104, s[8:9]
	v_cndmask_b32_e64 v104, v105, v172, s[10:11]
	v_fma_f32 v105, v131, v117, v135
	s_nop 0
	v_fma_f32 v79, v127, v79, v105
	s_nop 0
	v_fma_f32 v79, v123, v104, v79
	v_add_u32_e32 v104, 0xb0, v201
	v_cmp_gt_i32_e32 vcc, s68, v104
	s_and_b64 s[86:87], s[20:21], vcc
	v_add_u32_e32 v115, s59, v104
	s_and_saveexec_b64 s[88:89], s[86:87]
	s_cbranch_execz .LBB0_914
	v_mul_f32_e32 v104, 0xbfb8aa3b, v77
	v_exp_f32_e32 v104, v104
	s_nop 0
	v_add_f32_e32 v104, 1.0, v104
	v_rcp_f32_e32 v104, v104
	s_nop 0
	v_mul_f32_e32 v77, v77, v104
	v_mul_f32_e32 v77, v77, v79
	v_mul_f32_e32 v79, 0xbfb8aa3b, v76
	v_exp_f32_e32 v79, v79
	s_nop 0
	v_add_f32_e32 v79, 1.0, v79
	v_rcp_f32_e32 v79, v79
	s_nop 0
	v_mul_f32_e32 v76, v76, v79
	v_mul_f32_e32 v76, v76, v78
	v_mul_f32_e32 v78, 0xbfb8aa3b, v66
	v_exp_f32_e32 v78, v78
	s_nop 0
	v_add_f32_e32 v78, 1.0, v78
	v_rcp_f32_e32 v78, v78
	s_nop 0
	v_mul_f32_e32 v66, v66, v78
	v_mul_f32_e32 v66, v66, v67
	v_mul_f32_e32 v67, 0xbfb8aa3b, v64
	v_exp_f32_e32 v67, v67
	s_nop 0
	v_add_f32_e32 v67, 1.0, v67
	v_rcp_f32_e32 v67, v67
	s_nop 0
	v_mul_f32_e32 v64, v64, v67
	v_mul_f32_e32 v64, v64, v65
	v_cvt_pk_bf16_f32 v64, v64, v66
	v_mov_b64_e32 v[66:67], s[36:37]
	v_mad_i64_i32 v[66:67], s[72:73], v115, s69, v[66:67]
	v_lshl_add_u64 v[66:67], v[192:193], 1, v[66:67]
	v_cvt_pk_bf16_f32 v65, v76, v77
	global_store_dwordx2 v[66:67], v[64:65], off

;     __device__ __forceinline__ void operator()(const f32x4 (&acc)[2][2][4][2], const Unit& u, int wr, int wc, int fr, int fq) const {
;     ...
; #pragma unroll
;         for (int n = 0; n < 2; ++n) {
;             const f32x4 w0[2] = {wts[n][0][0], wts[n][1][0]}, w1[2] = {wts[n][0][1], wts[n][1][1]}, w2[2] = {wts[n][0][2], wts[n][1][2]}, bb[2] = {wts[n][0][3], wts[n][1][3]};
; #pragma unroll
;             for (int ai = 0; ai < 2; ++ai) {
;                 f32x4 pr1[2] = {zero4, zero4}, pr2[2] = {zero4, zero4};
;                 const bool hasprev = (wr == 1) || (ai == 1);
;                 const int pg = (wr == 1) ? ai * 2 : (ai - 1) * 2 + 1;
;                 if (hasprev && fr < 2) {
; #pragma unroll
;                     for (int bj = 0; bj < 2; ++bj) {
;                         pr2[bj] = *(const PG8_LAS f32x4*)(xch + ((pg * 2 + fr) * 256 + bj * 128 + colx + n * 4));
;                         pr1[bj] = *(const PG8_LAS f32x4*)(xch + ((pg * 2 + 1) * 256 + bj * 128 + colx + n * 4)); }
;                 }
; #pragma unroll
;                 for (int m = 0; m < 4; ++m) {
;                     f32x4 cur[2] = {acc[ai][0][m][n] * r2v[ai][m], acc[ai][1][m][n] * r2v[ai][m]};
;                     if (first && ai == 0 && wr == 0 && m == 0 && fr < 2) { cur[0] = zero4; cur[1] = zero4; }
;                     f32x4 r1[2], r2[2], av[2];
; #pragma unroll
;                     for (int bj = 0; bj < 2; ++bj)
; #pragma unroll
;                         for (int e = 0; e < 4; ++e) { r1[bj][e] = dpp_ror1(cur[bj][e]); r2[bj][e] = dpp_ror2(cur[bj][e]); }
; #pragma unroll
;                     for (int bj = 0; bj < 2; ++bj)
; #pragma unroll
;                         for (int e = 0; e < 4; ++e) { const float p1 = fr >= 1 ? r1[bj][e] : pr1[bj][e], p2 = fr >= 2 ? r2[bj][e] : pr2[bj][e];
;                             av[bj][e] = fma_s(w0[bj][e], p2, fma_s(w1[bj][e], p1, fma_s(w2[bj][e], cur[bj][e], bb[bj][e]))); }
;                     float o[4];
; #pragma unroll
;                     for (int e = 0; e < 4; ++e) o[e] = av[0][e] * sigmoid_f(av[0][e]) * av[1][e];
;                     const int lr = ai * HALF + wr * 64 + m * 16 + fr, t = t0 + lr;
;                     if (lr >= 2 && t < 4096) { u32x2 w; w.x = cvt_pk_bf16(o[0], o[1]); w.y = cvt_pk_bf16(o[2], o[3]);
;                         *(u32x2*)(gout + (size_t)(b * 4096 + t) * FF + j0 + n * 4) = w; }
.LBB0_916:
	s_or_b64 exec, exec, s[88:89]
	v_mov_b32_e32 v205, v204
	v_pk_mul_f32 v[60:61], v[60:61], v[204:205]
	v_mov_b32_e32 v116, v204
	v_mov_b32_e32 v117, v204
	v_cndmask_b32_e64 v131, v60, 0, s[78:79]
	v_pk_mul_f32 v[62:63], v[62:63], v[116:117]
	v_cndmask_b32_e64 v130, v61, 0, s[78:79]
	v_mov_b32_dpp v122, v131 row_ror:1 row_mask:0xf bank_mask:0xf
	v_cndmask_b32_e64 v127, v62, 0, s[78:79]
	v_mov_b32_dpp v123, v131 row_ror:2 row_mask:0xf bank_mask:0xf
	v_mov_b32_dpp v120, v130 row_ror:1 row_mask:0xf bank_mask:0xf
	s_waitcnt lgkmcnt(1)
	v_cndmask_b32_e64 v104, v122, v104, s[8:9]
	v_pk_mul_f32 v[58:59], v[58:59], v[116:117]
	v_pk_mul_f32 v[56:57], v[56:57], v[116:117]
	v_cndmask_b32_e64 v126, v63, 0, s[78:79]
	v_mov_b32_dpp v121, v130 row_ror:2 row_mask:0xf bank_mask:0xf
	v_mov_b32_dpp v118, v127 row_ror:1 row_mask:0xf bank_mask:0xf
	v_cndmask_b32_e64 v108, v108, v123, s[10:11]
	s_waitcnt vmcnt(4)
	v_fma_f32 v131, v96, v131, v100
	v_cndmask_b32_e64 v105, v120, v105, s[8:9]
	v_fma_f32 v104, v92, v104, v131
	v_cndmask_b32_e64 v129, v56, 0, s[78:79]
	v_mov_b32_dpp v119, v127 row_ror:2 row_mask:0xf bank_mask:0xf
	v_mov_b32_dpp v116, v126 row_ror:1 row_mask:0xf bank_mask:0xf
	v_fma_f32 v104, v88, v108, v104
	v_cndmask_b32_e64 v108, v109, v121, s[10:11]
	v_fma_f32 v109, v97, v130, v101
	v_cndmask_b32_e64 v106, v118, v106, s[8:9]
	v_fma_f32 v105, v93, v105, v109
	v_mov_b32_dpp v117, v126 row_ror:2 row_mask:0xf bank_mask:0xf
	v_mov_b32_dpp v62, v129 row_ror:1 row_mask:0xf bank_mask:0xf
	v_fma_f32 v105, v89, v108, v105
	v_cndmask_b32_e64 v108, v110, v119, s[10:11]
	v_fma_f32 v109, v98, v127, v102
	v_cndmask_b32_e64 v107, v116, v107, s[8:9]
	v_fma_f32 v106, v94, v106, v109
	v_cndmask_b32_e64 v128, v57, 0, s[78:79]
	v_mov_b32_dpp v63, v129 row_ror:2 row_mask:0xf bank_mask:0xf
	v_fma_f32 v106, v90, v108, v106
	v_cndmask_b32_e64 v108, v111, v117, s[10:11]
	v_fma_f32 v109, v99, v126, v103
	s_waitcnt lgkmcnt(0)
	v_cndmask_b32_e64 v64, v62, v64, s[8:9]
	v_fma_f32 v107, v95, v107, v109
	v_cndmask_b32_e64 v124, v59, 0, s[78:79]
	v_cndmask_b32_e64 v125, v58, 0, s[78:79]
	v_mov_b32_dpp v60, v128 row_ror:1 row_mask:0xf bank_mask:0xf
	v_mov_b32_dpp v61, v128 row_ror:2 row_mask:0xf bank_mask:0xf
	v_fma_f32 v107, v91, v108, v107
	v_cndmask_b32_e64 v76, v76, v63, s[10:11]
	s_waitcnt vmcnt(0)
	v_fma_f32 v108, v80, v129, v84
	v_mov_b32_dpp v58, v125 row_ror:1 row_mask:0xf bank_mask:0xf
	v_fma_f32 v64, v72, v64, v108
	v_mov_b32_dpp v56, v124 row_ror:1 row_mask:0xf bank_mask:0xf
	v_fma_f32 v64, v68, v76, v64
	v_cndmask_b32_e64 v65, v60, v65, s[8:9]
	v_cndmask_b32_e64 v76, v77, v61, s[10:11]
	v_fma_f32 v77, v81, v128, v85
	v_mov_b32_dpp v59, v125 row_ror:2 row_mask:0xf bank_mask:0xf
	v_fma_f32 v65, v73, v65, v77
	v_cndmask_b32_e64 v66, v58, v66, s[8:9]
	v_fma_f32 v77, v82, v125, v86
	v_cndmask_b32_e64 v67, v56, v67, s[8:9]
	v_mov_b32_dpp v57, v124 row_ror:2 row_mask:0xf bank_mask:0xf
	v_fma_f32 v65, v69, v76, v65
	v_cndmask_b32_e64 v76, v78, v59, s[10:11]
	v_fma_f32 v66, v74, v66, v77
	v_fma_f32 v77, v83, v124, v87
	s_nop 0
	v_fma_f32 v67, v75, v67, v77
	v_fma_f32 v66, v70, v76, v66
	v_cndmask_b32_e64 v76, v79, v57, s[10:11]
	v_fma_f32 v67, v71, v76, v67
	s_and_saveexec_b64 s[78:79], s[80:81]
	s_cbranch_execz .LBB0_918
	v_mul_f32_e32 v76, 0xbfb8aa3b, v107
	v_exp_f32_e32 v76, v76
	s_nop 0
	v_add_f32_e32 v76, 1.0, v76
	v_rcp_f32_e32 v76, v76
	s_nop 0
	v_mul_f32_e32 v76, v107, v76
	v_mul_f32_e32 v67, v76, v67
	v_mul_f32_e32 v76, 0xbfb8aa3b, v106
	v_exp_f32_e32 v76, v76
	s_nop 0
	v_add_f32_e32 v76, 1.0, v76
	v_rcp_f32_e32 v76, v76
	s_nop 0
	v_mul_f32_e32 v76, v106, v76
	v_mul_f32_e32 v66, v76, v66
	v_mul_f32_e32 v76, 0xbfb8aa3b, v105
	v_exp_f32_e32 v76, v76
	s_nop 0
	v_add_f32_e32 v76, 1.0, v76
	v_rcp_f32_e32 v76, v76
	s_nop 0
	v_mul_f32_e32 v76, v105, v76
	v_mul_f32_e32 v65, v76, v65
	v_mul_f32_e32 v76, 0xbfb8aa3b, v104
	v_exp_f32_e32 v76, v76
	s_nop 0
	v_add_f32_e32 v76, 1.0, v76
	v_rcp_f32_e32 v76, v76
	s_nop 0
	v_mul_f32_e32 v76, v104, v76
	v_mul_f32_e32 v64, v76, v64
	v_cvt_pk_bf16_f32 v64, v64, v65
	v_cvt_pk_bf16_f32 v65, v66, v67
	v_mov_b64_e32 v[66:67], s[36:37]
	v_mad_i64_i32 v[66:67], s[72:73], v199, s69, v[66:67]
	v_lshl_add_u64 v[66:67], v[192:193], 1, v[66:67]
	global_store_dwordx2 v[66:67], v[64:65], off offset:8
; __device__ __forceinline__ unsigned cvt_pk_bf16(float lo, float hi) { unsigned r; asm volatile("v_cvt_pk_bf16_f32 %0, %1, %2" : "=v"(r) : "v"(lo), "v"(hi)); return r; }
; __device__ __forceinline__ float sigmoid_f(float x) { return __builtin_amdgcn_rcpf(1.0f + __builtin_amdgcn_exp2f(-1.4426950408889634f * x)); }
; __device__ __forceinline__ float dpp_ror1(float v) { return __builtin_bit_cast(float, __builtin_amdgcn_update_dpp(0, __builtin_bit_cast(int, v), 0x121, 0xf, 0xf, false)); }
; __device__ __forceinline__ float dpp_ror2(float v) { return __builtin_bit_cast(float, __builtin_amdgcn_update_dpp(0, __builtin_bit_cast(int, v), 0x122, 0xf, 0xf, false)); }
; __device__ __forceinline__ float fma_s(float a, float b, float c) { float r; asm("v_fma_f32 %0, %1, %2, %3" : "=v"(r) : "v"(a), "v"(b), "v"(c)); return r; }
;     __device__ __forceinline__ void operator()(const f32x4 (&acc)[2][2][4][2], const Unit& u, int wr, int wc, int fr, int fq) const {
;     ...
;                 for (int m = 0; m < 4; ++m) {
;                     f32x4 cur[2] = {acc[ai][0][m][n] * r2v[ai][m], acc[ai][1][m][n] * r2v[ai][m]};
;                     if (first && ai == 0 && wr == 0 && m == 0 && fr < 2) { cur[0] = zero4; cur[1] = zero4; }
;                     f32x4 r1[2], r2[2], av[2];
; #pragma unroll
;                     for (int bj = 0; bj < 2; ++bj)
; #pragma unroll
;                         for (int e = 0; e < 4; ++e) { r1[bj][e] = dpp_ror1(cur[bj][e]); r2[bj][e] = dpp_ror2(cur[bj][e]); }
; #pragma unroll
;                     for (int bj = 0; bj < 2; ++bj)
; #pragma unroll
;                         for (int e = 0; e < 4; ++e) { const float p1 = fr >= 1 ? r1[bj][e] : pr1[bj][e], p2 = fr >= 2 ? r2[bj][e] : pr2[bj][e];
;                             av[bj][e] = fma_s(w0[bj][e], p2, fma_s(w1[bj][e], p1, fma_s(w2[bj][e], cur[bj][e], bb[bj][e]))); }
;                     float o[4];
; #pragma unroll
;                     for (int e = 0; e < 4; ++e) o[e] = av[0][e] * sigmoid_f(av[0][e]) * av[1][e];
;                     const int lr = ai * HALF + wr * 64 + m * 16 + fr, t = t0 + lr;
;                     if (lr >= 2 && t < 4096) { u32x2 w; w.x = cvt_pk_bf16(o[0], o[1]); w.y = cvt_pk_bf16(o[2], o[3]);
;                         *(u32x2*)(gout + (size_t)(b * 4096 + t) * FF + j0 + n * 4) = w; }
;                     pr1[0] = r1[0]; pr1[1] = r1[1]; pr2[0] = r2[0]; pr2[1] = r2[1];
.LBB0_918:
	s_or_b64 exec, exec, s[78:79]
	v_mov_b32_e32 v201, v200
	v_mov_b32_e32 v64, v200
	v_mov_b32_e32 v65, v200
	v_pk_mul_f32 v[106:107], v[54:55], v[64:65]
	v_pk_mul_f32 v[110:111], v[48:49], v[200:201]
	v_pk_mul_f32 v[104:105], v[52:53], v[200:201]
	v_pk_mul_f32 v[108:109], v[50:51], v[64:65]
	v_mov_b32_dpp v54, v110 row_ror:1 row_mask:0xf bank_mask:0xf
	v_mov_b32_dpp v64, v110 row_ror:2 row_mask:0xf bank_mask:0xf
	v_mov_b32_dpp v52, v111 row_ror:1 row_mask:0xf bank_mask:0xf
	v_cndmask_b32_e64 v62, v54, v62, s[8:9]
	v_mov_b32_dpp v53, v111 row_ror:2 row_mask:0xf bank_mask:0xf
	v_mov_b32_dpp v50, v108 row_ror:1 row_mask:0xf bank_mask:0xf
	v_cndmask_b32_e64 v63, v63, v64, s[10:11]
	v_fma_f32 v110, v80, v110, v84
	v_cndmask_b32_e64 v60, v52, v60, s[8:9]
	v_fma_f32 v62, v72, v62, v110
	v_mov_b32_dpp v51, v108 row_ror:2 row_mask:0xf bank_mask:0xf
	v_mov_b32_dpp v48, v109 row_ror:1 row_mask:0xf bank_mask:0xf
	v_fma_f32 v62, v68, v63, v62
	v_cndmask_b32_e64 v61, v61, v53, s[10:11]
	v_fma_f32 v63, v81, v111, v85
	v_cndmask_b32_e64 v58, v50, v58, s[8:9]
	v_fma_f32 v60, v73, v60, v63
	v_mov_b32_dpp v78, v104 row_ror:1 row_mask:0xf bank_mask:0xf
	v_mov_b32_dpp v79, v104 row_ror:2 row_mask:0xf bank_mask:0xf
	v_mov_b32_dpp v76, v105 row_ror:1 row_mask:0xf bank_mask:0xf
	v_mov_b32_dpp v77, v105 row_ror:2 row_mask:0xf bank_mask:0xf
	v_mov_b32_dpp v66, v106 row_ror:1 row_mask:0xf bank_mask:0xf
	v_mov_b32_dpp v67, v106 row_ror:2 row_mask:0xf bank_mask:0xf
	v_mov_b32_dpp v55, v107 row_ror:1 row_mask:0xf bank_mask:0xf
	v_mov_b32_dpp v65, v107 row_ror:2 row_mask:0xf bank_mask:0xf
	v_fma_f32 v104, v96, v104, v100
	v_fma_f32 v105, v97, v105, v101
	v_fma_f32 v106, v98, v106, v102
	v_fma_f32 v107, v99, v107, v103
	v_fma_f32 v60, v69, v61, v60
	v_cndmask_b32_e64 v59, v59, v51, s[10:11]
	v_fma_f32 v61, v82, v108, v86
	v_cndmask_b32_e64 v56, v48, v56, s[8:9]
	v_fma_f32 v58, v74, v58, v61
	v_mov_b32_dpp v49, v109 row_ror:2 row_mask:0xf bank_mask:0xf
	v_cndmask_b32_e64 v122, v78, v122, s[8:9]
	v_fma_f32 v104, v92, v122, v104
	v_cndmask_b32_e64 v120, v76, v120, s[8:9]
	v_fma_f32 v105, v93, v120, v105
	v_cndmask_b32_e64 v118, v66, v118, s[8:9]
	v_fma_f32 v106, v94, v118, v106
	v_cndmask_b32_e64 v116, v55, v116, s[8:9]
	v_fma_f32 v107, v95, v116, v107
	v_fma_f32 v58, v70, v59, v58
	v_fma_f32 v59, v83, v109, v87
	v_cndmask_b32_e64 v123, v123, v79, s[10:11]
	v_fma_f32 v56, v75, v56, v59
	v_fma_f32 v104, v88, v123, v104
	v_cndmask_b32_e64 v121, v121, v77, s[10:11]
	v_fma_f32 v105, v89, v121, v105
	v_cndmask_b32_e64 v119, v119, v67, s[10:11]
	v_fma_f32 v106, v90, v119, v106
	v_cndmask_b32_e64 v117, v117, v65, s[10:11]
	v_fma_f32 v107, v91, v117, v107
	v_cndmask_b32_e64 v57, v57, v49, s[10:11]
	v_fma_f32 v56, v71, v57, v56
	s_and_saveexec_b64 s[78:79], s[66:67]
	s_cbranch_execz .LBB0_920
	v_mul_f32_e32 v57, 0xbfb8aa3b, v107
	v_exp_f32_e32 v57, v57
	v_mul_f32_e32 v59, 0xbfb8aa3b, v104
	v_exp_f32_e32 v59, v59
	v_add_f32_e32 v57, 1.0, v57
	v_rcp_f32_e32 v57, v57
	v_add_f32_e32 v59, 1.0, v59
	v_rcp_f32_e32 v59, v59
	v_mul_f32_e32 v57, v107, v57
	v_mul_f32_e32 v57, v57, v56
	v_mul_f32_e32 v56, 0xbfb8aa3b, v106
	v_exp_f32_e32 v56, v56
	v_mul_f32_e32 v59, v104, v59
	v_mul_f32_e32 v59, v59, v62
	v_add_f32_e32 v56, 1.0, v56
	v_rcp_f32_e32 v56, v56
	s_nop 0
	v_mul_f32_e32 v56, v106, v56
	v_mul_f32_e32 v58, v56, v58
	v_mul_f32_e32 v56, 0xbfb8aa3b, v105
	v_exp_f32_e32 v56, v56
	s_nop 0
	v_add_f32_e32 v56, 1.0, v56
	v_rcp_f32_e32 v56, v56
	s_nop 0
	v_mul_f32_e32 v56, v105, v56
	v_mul_f32_e32 v56, v56, v60
	v_cvt_pk_bf16_f32 v56, v59, v56
	v_cvt_pk_bf16_f32 v57, v58, v57
	v_mov_b64_e32 v[58:59], s[36:37]
	v_mad_i64_i32 v[58:59], s[66:67], v197, s69, v[58:59]
	v_lshl_add_u64 v[58:59], v[192:193], 1, v[58:59]
	global_store_dwordx2 v[58:59], v[56:57], off offset:8
.LBB0_920:
	s_or_b64 exec, exec, s[78:79]
	v_mov_b32_e32 v199, v198
	v_pk_mul_f32 v[106:107], v[44:45], v[198:199]
	v_mov_b32_e32 v56, v198
	v_mov_b32_e32 v57, v198
	v_mov_b32_dpp v62, v106 row_ror:1 row_mask:0xf bank_mask:0xf
	v_pk_mul_f32 v[104:105], v[46:47], v[56:57]
	v_mov_b32_dpp v63, v106 row_ror:2 row_mask:0xf bank_mask:0xf
	v_mov_b32_dpp v60, v107 row_ror:1 row_mask:0xf bank_mask:0xf
	v_cndmask_b32_e64 v78, v62, v78, s[8:9]
	v_mov_b32_dpp v61, v107 row_ror:2 row_mask:0xf bank_mask:0xf
	v_mov_b32_dpp v58, v104 row_ror:1 row_mask:0xf bank_mask:0xf
	v_cndmask_b32_e64 v79, v79, v63, s[10:11]
	v_fma_f32 v106, v96, v106, v100
	v_cndmask_b32_e64 v76, v60, v76, s[8:9]
	v_fma_f32 v78, v92, v78, v106
	v_pk_mul_f32 v[108:109], v[42:43], v[56:57]
	v_pk_mul_f32 v[110:111], v[40:41], v[198:199]
	v_mov_b32_dpp v59, v104 row_ror:2 row_mask:0xf bank_mask:0xf
	v_mov_b32_dpp v47, v105 row_ror:1 row_mask:0xf bank_mask:0xf
	v_fma_f32 v78, v88, v79, v78
	v_cndmask_b32_e64 v77, v77, v61, s[10:11]
	v_fma_f32 v79, v97, v107, v101
	v_cndmask_b32_e64 v66, v58, v66, s[8:9]
	v_fma_f32 v76, v93, v76, v79
	v_mov_b32_dpp v57, v105 row_ror:2 row_mask:0xf bank_mask:0xf
	v_mov_b32_dpp v46, v110 row_ror:1 row_mask:0xf bank_mask:0xf
	v_fma_f32 v76, v89, v77, v76
	v_cndmask_b32_e64 v67, v67, v59, s[10:11]
	v_fma_f32 v77, v98, v104, v102
	v_cndmask_b32_e64 v55, v47, v55, s[8:9]
	v_fma_f32 v66, v94, v66, v77
	v_mov_b32_dpp v56, v110 row_ror:2 row_mask:0xf bank_mask:0xf
	v_mov_b32_dpp v44, v111 row_ror:1 row_mask:0xf bank_mask:0xf
	v_fma_f32 v66, v90, v67, v66
	v_cndmask_b32_e64 v65, v65, v57, s[10:11]
	v_fma_f32 v67, v99, v105, v103
	v_cndmask_b32_e64 v54, v46, v54, s[8:9]
	v_fma_f32 v55, v95, v55, v67
	v_mov_b32_dpp v45, v111 row_ror:2 row_mask:0xf bank_mask:0xf
	v_mov_b32_dpp v42, v108 row_ror:1 row_mask:0xf bank_mask:0xf
	v_fma_f32 v55, v91, v65, v55
	v_cndmask_b32_e64 v64, v64, v56, s[10:11]
	v_fma_f32 v65, v80, v110, v84
	v_cndmask_b32_e64 v52, v44, v52, s[8:9]
	v_fma_f32 v54, v72, v54, v65
	v_mov_b32_dpp v43, v108 row_ror:2 row_mask:0xf bank_mask:0xf
	v_mov_b32_dpp v40, v109 row_ror:1 row_mask:0xf bank_mask:0xf
	v_fma_f32 v54, v68, v64, v54
	v_cndmask_b32_e64 v53, v53, v45, s[10:11]
	v_fma_f32 v64, v81, v111, v85
	v_cndmask_b32_e64 v50, v42, v50, s[8:9]
	v_fma_f32 v52, v73, v52, v64
	v_fma_f32 v52, v69, v53, v52
	v_cndmask_b32_e64 v51, v51, v43, s[10:11]
	v_fma_f32 v53, v82, v108, v86
	v_cndmask_b32_e64 v48, v40, v48, s[8:9]
	v_fma_f32 v50, v74, v50, v53
	v_mov_b32_dpp v41, v109 row_ror:2 row_mask:0xf bank_mask:0xf
	v_fma_f32 v50, v70, v51, v50
	v_fma_f32 v51, v83, v109, v87
	v_cndmask_b32_e64 v49, v49, v41, s[10:11]
	v_fma_f32 v48, v75, v48, v51
	s_nop 0
	v_fma_f32 v48, v71, v49, v48
	s_and_saveexec_b64 s[66:67], s[0:1]
	s_cbranch_execz .LBB0_922
; __device__ __forceinline__ unsigned cvt_pk_bf16(float lo, float hi) { unsigned r; asm volatile("v_cvt_pk_bf16_f32 %0, %1, %2" : "=v"(r) : "v"(lo), "v"(hi)); return r; }
; __device__ __forceinline__ float sigmoid_f(float x) { return __builtin_amdgcn_rcpf(1.0f + __builtin_amdgcn_exp2f(-1.4426950408889634f * x)); }
; __device__ __forceinline__ float dpp_ror1(float v) { return __builtin_bit_cast(float, __builtin_amdgcn_update_dpp(0, __builtin_bit_cast(int, v), 0x121, 0xf, 0xf, false)); }
; __device__ __forceinline__ float dpp_ror2(float v) { return __builtin_bit_cast(float, __builtin_amdgcn_update_dpp(0, __builtin_bit_cast(int, v), 0x122, 0xf, 0xf, false)); }
; __device__ __forceinline__ float fma_s(float a, float b, float c) { float r; asm("v_fma_f32 %0, %1, %2, %3" : "=v"(r) : "v"(a), "v"(b), "v"(c)); return r; }
;     __device__ __forceinline__ void operator()(const f32x4 (&acc)[2][2][4][2], const Unit& u, int wr, int wc, int fr, int fq) const {
;     ...
;                 for (int m = 0; m < 4; ++m) {
;                     f32x4 cur[2] = {acc[ai][0][m][n] * r2v[ai][m], acc[ai][1][m][n] * r2v[ai][m]};
;                     if (first && ai == 0 && wr == 0 && m == 0 && fr < 2) { cur[0] = zero4; cur[1] = zero4; }
;                     f32x4 r1[2], r2[2], av[2];
; #pragma unroll
;                     for (int bj = 0; bj < 2; ++bj)
; #pragma unroll
;                         for (int e = 0; e < 4; ++e) { r1[bj][e] = dpp_ror1(cur[bj][e]); r2[bj][e] = dpp_ror2(cur[bj][e]); }
; #pragma unroll
;                     for (int bj = 0; bj < 2; ++bj)
; #pragma unroll
;                         for (int e = 0; e < 4; ++e) { const float p1 = fr >= 1 ? r1[bj][e] : pr1[bj][e], p2 = fr >= 2 ? r2[bj][e] : pr2[bj][e];
;                             av[bj][e] = fma_s(w0[bj][e], p2, fma_s(w1[bj][e], p1, fma_s(w2[bj][e], cur[bj][e], bb[bj][e]))); }
;                     float o[4];
; #pragma unroll
;                     for (int e = 0; e < 4; ++e) o[e] = av[0][e] * sigmoid_f(av[0][e]) * av[1][e];
;                     const int lr = ai * HALF + wr * 64 + m * 16 + fr, t = t0 + lr;
;                     if (lr >= 2 && t < 4096) { u32x2 w; w.x = cvt_pk_bf16(o[0], o[1]); w.y = cvt_pk_bf16(o[2], o[3]);
;                         *(u32x2*)(gout + (size_t)(b * 4096 + t) * FF + j0 + n * 4) = w; }
;                     pr1[0] = r1[0]; pr1[1] = r1[1]; pr2[0] = r2[0]; pr2[1] = r2[1];
	v_mul_f32_e32 v49, 0xbfb8aa3b, v55
	v_exp_f32_e32 v49, v49
	v_mul_f32_e32 v51, 0xbfb8aa3b, v78
	v_exp_f32_e32 v51, v51
	v_add_f32_e32 v49, 1.0, v49
	v_rcp_f32_e32 v49, v49
	v_add_f32_e32 v51, 1.0, v51
	v_rcp_f32_e32 v51, v51
	v_mul_f32_e32 v49, v55, v49
	v_mul_f32_e32 v49, v49, v48
	v_mul_f32_e32 v48, 0xbfb8aa3b, v66
	v_exp_f32_e32 v48, v48
	v_mul_f32_e32 v51, v78, v51
	v_mul_f32_e32 v51, v51, v54
	v_add_f32_e32 v48, 1.0, v48
	v_rcp_f32_e32 v48, v48
	s_nop 0
	v_mul_f32_e32 v48, v66, v48
	v_mul_f32_e32 v50, v48, v50
	v_mul_f32_e32 v48, 0xbfb8aa3b, v76
	v_exp_f32_e32 v48, v48
	s_nop 0
	v_add_f32_e32 v48, 1.0, v48
	v_rcp_f32_e32 v48, v48
	s_nop 0
	v_mul_f32_e32 v48, v76, v48
	v_mul_f32_e32 v48, v48, v52
	v_cvt_pk_bf16_f32 v48, v51, v48
	v_cvt_pk_bf16_f32 v49, v50, v49
	v_mov_b64_e32 v[50:51], s[36:37]
	v_mad_i64_i32 v[50:51], s[0:1], v195, s69, v[50:51]
	v_lshl_add_u64 v[50:51], v[192:193], 1, v[50:51]
	global_store_dwordx2 v[50:51], v[48:49], off offset:8
.LBB0_922:
	s_or_b64 exec, exec, s[66:67]
	v_mov_b32_e32 v197, v196
	v_pk_mul_f32 v[36:37], v[36:37], v[196:197]
	v_pk_mul_f32 v[50:51], v[32:33], v[196:197]
	v_mov_b32_e32 v48, v196
	v_mov_b32_e32 v49, v196
	v_mov_b32_dpp v32, v36 row_ror:1 row_mask:0xf bank_mask:0xf
	v_pk_mul_f32 v[38:39], v[38:39], v[48:49]
	v_pk_mul_f32 v[48:49], v[34:35], v[48:49]
	v_mov_b32_dpp v33, v36 row_ror:2 row_mask:0xf bank_mask:0xf
	v_cndmask_b32_e64 v32, v32, v62, s[8:9]
	v_mov_b32_dpp v34, v37 row_ror:1 row_mask:0xf bank_mask:0xf
	v_cndmask_b32_e64 v33, v63, v33, s[10:11]
	v_fma_f32 v36, v96, v36, v100
	v_mov_b32_dpp v35, v37 row_ror:2 row_mask:0xf bank_mask:0xf
	v_fma_f32 v32, v92, v32, v36
	v_fma_f32 v32, v88, v33, v32
	v_cndmask_b32_e64 v33, v34, v60, s[8:9]
	v_mov_b32_dpp v52, v38 row_ror:1 row_mask:0xf bank_mask:0xf
	v_cndmask_b32_e64 v34, v61, v35, s[10:11]
	v_fma_f32 v35, v97, v37, v101
	v_mov_b32_dpp v53, v38 row_ror:2 row_mask:0xf bank_mask:0xf
	v_fma_f32 v33, v93, v33, v35
	v_fma_f32 v33, v89, v34, v33
	v_cndmask_b32_e64 v34, v52, v58, s[8:9]
	v_mov_b32_dpp v54, v39 row_ror:1 row_mask:0xf bank_mask:0xf
	v_cndmask_b32_e64 v35, v59, v53, s[10:11]
	v_fma_f32 v36, v98, v38, v102
	v_mov_b32_dpp v55, v39 row_ror:2 row_mask:0xf bank_mask:0xf
	v_fma_f32 v34, v94, v34, v36
	v_fma_f32 v34, v90, v35, v34
	v_cndmask_b32_e64 v35, v54, v47, s[8:9]
	v_mov_b32_dpp v64, v50 row_ror:1 row_mask:0xf bank_mask:0xf
	v_cndmask_b32_e64 v36, v57, v55, s[10:11]
	v_fma_f32 v37, v99, v39, v103
	v_mov_b32_dpp v65, v50 row_ror:2 row_mask:0xf bank_mask:0xf
	v_fma_f32 v35, v95, v35, v37
	v_fma_f32 v36, v91, v36, v35
	v_cndmask_b32_e64 v35, v64, v46, s[8:9]
	v_mov_b32_dpp v66, v51 row_ror:1 row_mask:0xf bank_mask:0xf
	v_cndmask_b32_e64 v37, v56, v65, s[10:11]
	v_fma_f32 v38, v80, v50, v84
	v_mov_b32_dpp v67, v51 row_ror:2 row_mask:0xf bank_mask:0xf
	v_fma_f32 v35, v72, v35, v38
	v_fma_f32 v35, v68, v37, v35
	v_cndmask_b32_e64 v37, v66, v44, s[8:9]
	v_mov_b32_dpp v76, v48 row_ror:1 row_mask:0xf bank_mask:0xf
	v_cndmask_b32_e64 v38, v45, v67, s[10:11]
	v_fma_f32 v39, v81, v51, v85
	v_mov_b32_dpp v77, v48 row_ror:2 row_mask:0xf bank_mask:0xf
	v_fma_f32 v37, v73, v37, v39
	v_fma_f32 v37, v69, v38, v37
	v_cndmask_b32_e64 v38, v76, v42, s[8:9]
	v_mov_b32_dpp v78, v49 row_ror:1 row_mask:0xf bank_mask:0xf
	v_cndmask_b32_e64 v39, v43, v77, s[10:11]
	v_fma_f32 v42, v82, v48, v86
	v_mov_b32_dpp v79, v49 row_ror:2 row_mask:0xf bank_mask:0xf
	v_fma_f32 v38, v74, v38, v42
	s_nop 0
	v_fma_f32 v38, v70, v39, v38
	v_cndmask_b32_e64 v39, v78, v40, s[8:9]
	v_cndmask_b32_e64 v40, v41, v79, s[10:11]
	v_fma_f32 v41, v83, v49, v87
	s_nop 0
	v_fma_f32 v39, v75, v39, v41
	s_nop 0
	v_fma_f32 v39, v71, v40, v39
	s_and_saveexec_b64 s[0:1], s[64:65]
	s_cbranch_execz .LBB0_924
	v_mul_f32_e32 v40, 0xbfb8aa3b, v36
	v_exp_f32_e32 v40, v40
	v_mul_f32_e32 v41, 0xbfb8aa3b, v34
	v_mul_f32_e32 v42, 0xbfb8aa3b, v33
	v_exp_f32_e32 v41, v41
	v_add_f32_e32 v40, 1.0, v40
	v_rcp_f32_e32 v40, v40
	v_exp_f32_e32 v42, v42
	v_add_f32_e32 v41, 1.0, v41
	v_rcp_f32_e32 v41, v41
	v_mul_f32_e32 v36, v36, v40
	v_mul_f32_e32 v36, v36, v39
	v_mul_f32_e32 v39, 0xbfb8aa3b, v32
	v_exp_f32_e32 v39, v39
	v_add_f32_e32 v40, 1.0, v42
	v_rcp_f32_e32 v40, v40
	v_mul_f32_e32 v34, v34, v41
	v_add_f32_e32 v39, 1.0, v39
	v_rcp_f32_e32 v39, v39
	v_mul_f32_e32 v33, v33, v40
	v_mul_f32_e32 v34, v34, v38
	v_mul_f32_e32 v33, v33, v37
	v_mul_f32_e32 v32, v32, v39
	v_mul_f32_e32 v32, v32, v35
	v_cvt_pk_bf16_f32 v32, v32, v33
	v_cvt_pk_bf16_f32 v33, v34, v36
	v_mov_b64_e32 v[34:35], s[36:37]
	v_mad_i64_i32 v[34:35], s[64:65], v227, s69, v[34:35]
	v_lshl_add_u64 v[34:35], v[192:193], 1, v[34:35]
	global_store_dwordx2 v[34:35], v[32:33], off offset:8

; #define PG8_LAS __attribute__((address_space(3)))
; __device__ __forceinline__ float sigmoid_f(float x) { return __builtin_amdgcn_rcpf(1.0f + __builtin_amdgcn_exp2f(-1.4426950408889634f * x)); }
;     __device__ __forceinline__ void operator()(const f32x4 (&acc)[2][2][4][2], const Unit& u, int wr, int wc, int fr, int fq) const {
;     ...
;             for (int ai = 0; ai < 2; ++ai) {
;                 f32x4 pr1[2] = {zero4, zero4}, pr2[2] = {zero4, zero4};
;                 const bool hasprev = (wr == 1) || (ai == 1);
;                 const int pg = (wr == 1) ? ai * 2 : (ai - 1) * 2 + 1;
;                 if (hasprev && fr < 2) {
; #pragma unroll
;                     for (int bj = 0; bj < 2; ++bj) {
;                         pr2[bj] = *(const PG8_LAS f32x4*)(xch + ((pg * 2 + fr) * 256 + bj * 128 + colx + n * 4));
;                         pr1[bj] = *(const PG8_LAS f32x4*)(xch + ((pg * 2 + 1) * 256 + bj * 128 + colx + n * 4)); }
;                 }
; #pragma unroll
;                 for (int m = 0; m < 4; ++m) {
;                     f32x4 cur[2] = {acc[ai][0][m][n] * r2v[ai][m], acc[ai][1][m][n] * r2v[ai][m]};
;                     if (first && ai == 0 && wr == 0 && m == 0 && fr < 2) { cur[0] = zero4; cur[1] = zero4; }
;                     f32x4 r1[2], r2[2], av[2];
; #pragma unroll
;                     for (int bj = 0; bj < 2; ++bj)
; #pragma unroll
;                         for (int e = 0; e < 4; ++e) { r1[bj][e] = dpp_ror1(cur[bj][e]); r2[bj][e] = dpp_ror2(cur[bj][e]); }
; #pragma unroll
;                     for (int bj = 0; bj < 2; ++bj)
; #pragma unroll
;                         for (int e = 0; e < 4; ++e) { const float p1 = fr >= 1 ? r1[bj][e] : pr1[bj][e], p2 = fr >= 2 ? r2[bj][e] : pr2[bj][e];
;                             av[bj][e] = fma_s(w0[bj][e], p2, fma_s(w1[bj][e], p1, fma_s(w2[bj][e], cur[bj][e], bb[bj][e]))); }
;                     float o[4];
; #pragma unroll
;                     for (int e = 0; e < 4; ++e) o[e] = av[0][e] * sigmoid_f(av[0][e]) * av[1][e];
;                     const int lr = ai * HALF + wr * 64 + m * 16 + fr, t = t0 + lr;
;                     if (lr >= 2 && t < 4096) { u32x2 w; w.x = cvt_pk_bf16(o[0], o[1]); w.y = cvt_pk_bf16(o[2], o[3]);
;                         *(u32x2*)(gout + (size_t)(b * 4096 + t) * FF + j0 + n * 4) = w; }
;                     pr1[0] = r1[0]; pr1[1] = r1[1]; pr2[0] = r2[0]; pr2[1] = r2[1];
.LBB0_926:
	s_or_b64 exec, exec, s[0:1]
	v_mov_b32_e32 v203, v202
	v_pk_mul_f32 v[58:59], v[28:29], v[202:203]
	v_mov_b32_e32 v48, v202
	v_mov_b32_e32 v49, v202
	v_mov_b32_dpp v54, v58 row_ror:1 row_mask:0xf bank_mask:0xf
	v_pk_mul_f32 v[56:57], v[30:31], v[48:49]
	v_mov_b32_dpp v55, v58 row_ror:2 row_mask:0xf bank_mask:0xf
	v_mov_b32_dpp v52, v59 row_ror:1 row_mask:0xf bank_mask:0xf
	s_waitcnt lgkmcnt(1)
	v_cndmask_b32_e64 v40, v54, v40, s[8:9]
	v_mov_b32_dpp v53, v59 row_ror:2 row_mask:0xf bank_mask:0xf
	v_mov_b32_dpp v50, v56 row_ror:1 row_mask:0xf bank_mask:0xf
	v_cndmask_b32_e64 v44, v44, v55, s[10:11]
	v_fma_f32 v58, v96, v58, v100
	v_cndmask_b32_e64 v41, v52, v41, s[8:9]
	v_fma_f32 v40, v92, v40, v58
	v_pk_mul_f32 v[60:61], v[26:27], v[48:49]
	v_pk_mul_f32 v[62:63], v[24:25], v[202:203]
	v_mov_b32_dpp v51, v56 row_ror:2 row_mask:0xf bank_mask:0xf
	v_mov_b32_dpp v31, v57 row_ror:1 row_mask:0xf bank_mask:0xf
	v_fma_f32 v40, v88, v44, v40
	v_cndmask_b32_e64 v44, v45, v53, s[10:11]
	v_fma_f32 v45, v97, v59, v101
	v_cndmask_b32_e64 v42, v50, v42, s[8:9]
	v_fma_f32 v41, v93, v41, v45
	v_mov_b32_dpp v49, v57 row_ror:2 row_mask:0xf bank_mask:0xf
	v_mov_b32_dpp v30, v62 row_ror:1 row_mask:0xf bank_mask:0xf
	v_fma_f32 v41, v89, v44, v41
	v_cndmask_b32_e64 v44, v46, v51, s[10:11]
	v_fma_f32 v45, v98, v56, v102
	v_cndmask_b32_e64 v43, v31, v43, s[8:9]
	v_fma_f32 v42, v94, v42, v45
	v_mov_b32_dpp v48, v62 row_ror:2 row_mask:0xf bank_mask:0xf
	v_fma_f32 v42, v90, v44, v42
	v_cndmask_b32_e64 v44, v47, v49, s[10:11]
	v_fma_f32 v45, v99, v57, v103
	s_waitcnt lgkmcnt(0)
	v_cndmask_b32_e64 v32, v30, v32, s[8:9]
	v_fma_f32 v43, v95, v43, v45
	v_mov_b32_dpp v28, v63 row_ror:1 row_mask:0xf bank_mask:0xf
	v_mov_b32_dpp v29, v63 row_ror:2 row_mask:0xf bank_mask:0xf
	v_fma_f32 v43, v91, v44, v43
	v_cndmask_b32_e64 v36, v36, v48, s[10:11]
	v_fma_f32 v44, v80, v62, v84
	v_mov_b32_dpp v26, v60 row_ror:1 row_mask:0xf bank_mask:0xf
	v_fma_f32 v32, v72, v32, v44
	v_mov_b32_dpp v24, v61 row_ror:1 row_mask:0xf bank_mask:0xf
	v_fma_f32 v32, v68, v36, v32
	v_cndmask_b32_e64 v33, v28, v33, s[8:9]
	v_cndmask_b32_e64 v36, v37, v29, s[10:11]
	v_fma_f32 v37, v81, v63, v85
	v_mov_b32_dpp v27, v60 row_ror:2 row_mask:0xf bank_mask:0xf
	v_fma_f32 v33, v73, v33, v37
	v_cndmask_b32_e64 v34, v26, v34, s[8:9]
	v_fma_f32 v37, v82, v60, v86
	v_cndmask_b32_e64 v35, v24, v35, s[8:9]
	v_mov_b32_dpp v25, v61 row_ror:2 row_mask:0xf bank_mask:0xf
	v_fma_f32 v33, v69, v36, v33
	v_cndmask_b32_e64 v36, v38, v27, s[10:11]
	v_fma_f32 v34, v74, v34, v37
	v_fma_f32 v37, v83, v61, v87
	s_nop 0
	v_fma_f32 v35, v75, v35, v37
	v_fma_f32 v34, v70, v36, v34
	v_cndmask_b32_e64 v36, v39, v25, s[10:11]
	v_fma_f32 v35, v71, v36, v35
	s_and_saveexec_b64 s[0:1], s[76:77]
	s_cbranch_execz .LBB0_928
	v_mul_f32_e32 v36, 0xbfb8aa3b, v43
	v_exp_f32_e32 v36, v36
	v_mul_f32_e32 v37, 0xbfb8aa3b, v42
	v_mul_f32_e32 v38, 0xbfb8aa3b, v41
	v_exp_f32_e32 v37, v37
	v_add_f32_e32 v36, 1.0, v36
	v_rcp_f32_e32 v36, v36
	v_exp_f32_e32 v38, v38
	v_add_f32_e32 v37, 1.0, v37
	v_rcp_f32_e32 v37, v37
	v_mul_f32_e32 v36, v43, v36
	v_mul_f32_e32 v35, v36, v35
	v_mul_f32_e32 v36, 0xbfb8aa3b, v40
	v_exp_f32_e32 v36, v36
	v_add_f32_e32 v38, 1.0, v38
	v_rcp_f32_e32 v38, v38
	v_mul_f32_e32 v37, v42, v37
	v_add_f32_e32 v36, 1.0, v36
	v_rcp_f32_e32 v36, v36
	v_mul_f32_e32 v34, v37, v34
	v_mul_f32_e32 v37, v41, v38
	v_mul_f32_e32 v33, v37, v33
	v_mul_f32_e32 v36, v40, v36
	v_mul_f32_e32 v32, v36, v32
	v_cvt_pk_bf16_f32 v32, v32, v33
	v_cvt_pk_bf16_f32 v33, v34, v35
	v_mov_b64_e32 v[34:35], s[36:37]
	v_mad_i64_i32 v[34:35], s[64:65], v141, s69, v[34:35]
	v_lshl_add_u64 v[34:35], v[192:193], 1, v[34:35]
	global_store_dwordx2 v[34:35], v[32:33], off offset:8
.LBB0_928:
	s_or_b64 exec, exec, s[0:1]
	v_mov_b32_e32 v141, v140
	v_mov_b32_e32 v32, v140
	v_mov_b32_e32 v33, v140
	v_pk_mul_f32 v[42:43], v[22:23], v[32:33]
	v_pk_mul_f32 v[46:47], v[16:17], v[140:141]
	v_pk_mul_f32 v[40:41], v[20:21], v[140:141]
	v_pk_mul_f32 v[44:45], v[18:19], v[32:33]
	v_mov_b32_dpp v23, v43 row_ror:1 row_mask:0xf bank_mask:0xf
	v_mov_b32_dpp v22, v46 row_ror:1 row_mask:0xf bank_mask:0xf
	v_mov_b32_dpp v33, v43 row_ror:2 row_mask:0xf bank_mask:0xf
	v_mov_b32_dpp v32, v46 row_ror:2 row_mask:0xf bank_mask:0xf
	v_mov_b32_dpp v20, v47 row_ror:1 row_mask:0xf bank_mask:0xf
	v_cndmask_b32_e64 v31, v23, v31, s[8:9]
	v_fma_f32 v43, v99, v43, v103
	v_cndmask_b32_e64 v30, v22, v30, s[8:9]
	v_mov_b32_dpp v21, v47 row_ror:2 row_mask:0xf bank_mask:0xf
	v_mov_b32_dpp v18, v44 row_ror:1 row_mask:0xf bank_mask:0xf
	v_fma_f32 v31, v95, v31, v43
	v_cndmask_b32_e64 v43, v48, v32, s[10:11]
	v_fma_f32 v46, v80, v46, v84
	v_cndmask_b32_e64 v28, v20, v28, s[8:9]
	v_fma_f32 v30, v72, v30, v46
	v_mov_b32_dpp v19, v44 row_ror:2 row_mask:0xf bank_mask:0xf
	v_mov_b32_dpp v16, v45 row_ror:1 row_mask:0xf bank_mask:0xf
	v_fma_f32 v30, v68, v43, v30
	v_cndmask_b32_e64 v29, v29, v21, s[10:11]
	v_fma_f32 v43, v81, v47, v85
	v_cndmask_b32_e64 v26, v18, v26, s[8:9]
	v_fma_f32 v28, v73, v28, v43
	v_mov_b32_dpp v38, v40 row_ror:1 row_mask:0xf bank_mask:0xf
	v_mov_b32_dpp v39, v40 row_ror:2 row_mask:0xf bank_mask:0xf
	v_mov_b32_dpp v36, v41 row_ror:1 row_mask:0xf bank_mask:0xf
	v_mov_b32_dpp v37, v41 row_ror:2 row_mask:0xf bank_mask:0xf
	v_mov_b32_dpp v34, v42 row_ror:1 row_mask:0xf bank_mask:0xf
	v_mov_b32_dpp v35, v42 row_ror:2 row_mask:0xf bank_mask:0xf
	v_fma_f32 v40, v96, v40, v100
	v_fma_f32 v41, v97, v41, v101
	v_fma_f32 v42, v98, v42, v102
	v_fma_f32 v28, v69, v29, v28
	v_cndmask_b32_e64 v27, v27, v19, s[10:11]
	v_fma_f32 v29, v82, v44, v86
	v_cndmask_b32_e64 v24, v16, v24, s[8:9]
	v_fma_f32 v26, v74, v26, v29
	v_mov_b32_dpp v17, v45 row_ror:2 row_mask:0xf bank_mask:0xf
	v_cndmask_b32_e64 v54, v38, v54, s[8:9]
	v_fma_f32 v40, v92, v54, v40
	v_cndmask_b32_e64 v52, v36, v52, s[8:9]
	v_fma_f32 v41, v93, v52, v41
	v_cndmask_b32_e64 v50, v34, v50, s[8:9]
	v_fma_f32 v42, v94, v50, v42
	v_fma_f32 v26, v70, v27, v26
	v_fma_f32 v27, v83, v45, v87
	v_cndmask_b32_e64 v55, v55, v39, s[10:11]
	v_fma_f32 v24, v75, v24, v27
	v_fma_f32 v40, v88, v55, v40
	v_cndmask_b32_e64 v53, v53, v37, s[10:11]
	v_fma_f32 v41, v89, v53, v41
	v_cndmask_b32_e64 v51, v51, v35, s[10:11]
	v_fma_f32 v42, v90, v51, v42
	v_cndmask_b32_e64 v49, v49, v33, s[10:11]
	v_fma_f32 v31, v91, v49, v31
	v_cndmask_b32_e64 v25, v25, v17, s[10:11]
	v_fma_f32 v24, v71, v25, v24
	s_and_saveexec_b64 s[0:1], s[82:83]
	s_cbranch_execz .LBB0_930
; __device__ __forceinline__ unsigned cvt_pk_bf16(float lo, float hi) { unsigned r; asm volatile("v_cvt_pk_bf16_f32 %0, %1, %2" : "=v"(r) : "v"(lo), "v"(hi)); return r; }
; __device__ __forceinline__ float sigmoid_f(float x) { return __builtin_amdgcn_rcpf(1.0f + __builtin_amdgcn_exp2f(-1.4426950408889634f * x)); }
; __device__ __forceinline__ float dpp_ror1(float v) { return __builtin_bit_cast(float, __builtin_amdgcn_update_dpp(0, __builtin_bit_cast(int, v), 0x121, 0xf, 0xf, false)); }
; __device__ __forceinline__ float dpp_ror2(float v) { return __builtin_bit_cast(float, __builtin_amdgcn_update_dpp(0, __builtin_bit_cast(int, v), 0x122, 0xf, 0xf, false)); }
; __device__ __forceinline__ float fma_s(float a, float b, float c) { float r; asm("v_fma_f32 %0, %1, %2, %3" : "=v"(r) : "v"(a), "v"(b), "v"(c)); return r; }
;     __device__ __forceinline__ void operator()(const f32x4 (&acc)[2][2][4][2], const Unit& u, int wr, int wc, int fr, int fq) const {
;     ...
;                 for (int m = 0; m < 4; ++m) {
;                     f32x4 cur[2] = {acc[ai][0][m][n] * r2v[ai][m], acc[ai][1][m][n] * r2v[ai][m]};
;                     if (first && ai == 0 && wr == 0 && m == 0 && fr < 2) { cur[0] = zero4; cur[1] = zero4; }
;                     f32x4 r1[2], r2[2], av[2];
; #pragma unroll
;                     for (int bj = 0; bj < 2; ++bj)
; #pragma unroll
;                         for (int e = 0; e < 4; ++e) { r1[bj][e] = dpp_ror1(cur[bj][e]); r2[bj][e] = dpp_ror2(cur[bj][e]); }
; #pragma unroll
;                     for (int bj = 0; bj < 2; ++bj)
; #pragma unroll
;                         for (int e = 0; e < 4; ++e) { const float p1 = fr >= 1 ? r1[bj][e] : pr1[bj][e], p2 = fr >= 2 ? r2[bj][e] : pr2[bj][e];
;                             av[bj][e] = fma_s(w0[bj][e], p2, fma_s(w1[bj][e], p1, fma_s(w2[bj][e], cur[bj][e], bb[bj][e]))); }
;                     float o[4];
; #pragma unroll
;                     for (int e = 0; e < 4; ++e) o[e] = av[0][e] * sigmoid_f(av[0][e]) * av[1][e];
;                     const int lr = ai * HALF + wr * 64 + m * 16 + fr, t = t0 + lr;
;                     if (lr >= 2 && t < 4096) { u32x2 w; w.x = cvt_pk_bf16(o[0], o[1]); w.y = cvt_pk_bf16(o[2], o[3]);
;                         *(u32x2*)(gout + (size_t)(b * 4096 + t) * FF + j0 + n * 4) = w; }
;                     pr1[0] = r1[0]; pr1[1] = r1[1]; pr2[0] = r2[0]; pr2[1] = r2[1];
	v_mul_f32_e32 v25, 0xbfb8aa3b, v31
	v_exp_f32_e32 v25, v25
	v_mul_f32_e32 v27, 0xbfb8aa3b, v42
	v_mul_f32_e32 v29, 0xbfb8aa3b, v41
	v_exp_f32_e32 v27, v27
	v_add_f32_e32 v25, 1.0, v25
	v_rcp_f32_e32 v25, v25
	v_exp_f32_e32 v29, v29
	v_add_f32_e32 v27, 1.0, v27
	v_rcp_f32_e32 v27, v27
	v_mul_f32_e32 v25, v31, v25
	v_mul_f32_e32 v25, v25, v24
	v_mul_f32_e32 v24, 0xbfb8aa3b, v40
	v_exp_f32_e32 v24, v24
	v_add_f32_e32 v29, 1.0, v29
	v_rcp_f32_e32 v29, v29
	v_mul_f32_e32 v27, v42, v27
	v_add_f32_e32 v24, 1.0, v24
	v_rcp_f32_e32 v24, v24
	v_mul_f32_e32 v26, v27, v26
	v_mul_f32_e32 v27, v41, v29
	v_mul_f32_e32 v27, v27, v28
	v_mul_f32_e32 v24, v40, v24
	v_mul_f32_e32 v24, v24, v30
	v_cvt_pk_bf16_f32 v24, v24, v27
	v_cvt_pk_bf16_f32 v25, v26, v25
	v_mov_b64_e32 v[26:27], s[36:37]
	v_mad_i64_i32 v[26:27], s[64:65], v113, s69, v[26:27]
	v_lshl_add_u64 v[26:27], v[192:193], 1, v[26:27]
	global_store_dwordx2 v[26:27], v[24:25], off offset:8
.LBB0_930:
	s_or_b64 exec, exec, s[0:1]
	v_mov_b32_e32 v113, v112
	v_pk_mul_f32 v[42:43], v[12:13], v[112:113]
	v_mov_b32_e32 v24, v112
	v_mov_b32_e32 v25, v112
	v_mov_b32_dpp v30, v42 row_ror:1 row_mask:0xf bank_mask:0xf
	v_pk_mul_f32 v[40:41], v[14:15], v[24:25]
	v_mov_b32_dpp v31, v42 row_ror:2 row_mask:0xf bank_mask:0xf
	v_mov_b32_dpp v28, v43 row_ror:1 row_mask:0xf bank_mask:0xf
	v_cndmask_b32_e64 v38, v30, v38, s[8:9]
	v_mov_b32_dpp v29, v43 row_ror:2 row_mask:0xf bank_mask:0xf
	v_mov_b32_dpp v26, v40 row_ror:1 row_mask:0xf bank_mask:0xf
	v_cndmask_b32_e64 v39, v39, v31, s[10:11]
	v_fma_f32 v42, v96, v42, v100
	v_cndmask_b32_e64 v36, v28, v36, s[8:9]
	v_fma_f32 v38, v92, v38, v42
	v_pk_mul_f32 v[44:45], v[10:11], v[24:25]
	v_pk_mul_f32 v[46:47], v[8:9], v[112:113]
	v_mov_b32_dpp v27, v40 row_ror:2 row_mask:0xf bank_mask:0xf
	v_mov_b32_dpp v15, v41 row_ror:1 row_mask:0xf bank_mask:0xf
	v_fma_f32 v38, v88, v39, v38
	v_cndmask_b32_e64 v37, v37, v29, s[10:11]
	v_fma_f32 v39, v97, v43, v101
	v_cndmask_b32_e64 v34, v26, v34, s[8:9]
	v_fma_f32 v36, v93, v36, v39
	v_mov_b32_dpp v25, v41 row_ror:2 row_mask:0xf bank_mask:0xf
	v_mov_b32_dpp v14, v46 row_ror:1 row_mask:0xf bank_mask:0xf
	v_fma_f32 v36, v89, v37, v36
	v_cndmask_b32_e64 v35, v35, v27, s[10:11]
	v_fma_f32 v37, v98, v40, v102
	v_cndmask_b32_e64 v23, v15, v23, s[8:9]
	v_fma_f32 v34, v94, v34, v37
	v_mov_b32_dpp v24, v46 row_ror:2 row_mask:0xf bank_mask:0xf
	v_mov_b32_dpp v12, v47 row_ror:1 row_mask:0xf bank_mask:0xf
	v_fma_f32 v34, v90, v35, v34
	v_cndmask_b32_e64 v33, v33, v25, s[10:11]
	v_fma_f32 v35, v99, v41, v103
	v_cndmask_b32_e64 v22, v14, v22, s[8:9]
	v_fma_f32 v23, v95, v23, v35
	v_mov_b32_dpp v13, v47 row_ror:2 row_mask:0xf bank_mask:0xf
	v_mov_b32_dpp v10, v44 row_ror:1 row_mask:0xf bank_mask:0xf
	v_fma_f32 v23, v91, v33, v23
	v_cndmask_b32_e64 v32, v32, v24, s[10:11]
	v_fma_f32 v33, v80, v46, v84
	v_cndmask_b32_e64 v20, v12, v20, s[8:9]
	v_fma_f32 v22, v72, v22, v33
	v_mov_b32_dpp v11, v44 row_ror:2 row_mask:0xf bank_mask:0xf
	v_mov_b32_dpp v8, v45 row_ror:1 row_mask:0xf bank_mask:0xf
	v_fma_f32 v22, v68, v32, v22
	v_cndmask_b32_e64 v21, v21, v13, s[10:11]
	v_fma_f32 v32, v81, v47, v85
	v_cndmask_b32_e64 v18, v10, v18, s[8:9]
	v_fma_f32 v20, v73, v20, v32
	v_fma_f32 v20, v69, v21, v20
	v_cndmask_b32_e64 v19, v19, v11, s[10:11]
	v_fma_f32 v21, v82, v44, v86
	v_cndmask_b32_e64 v16, v8, v16, s[8:9]
	v_fma_f32 v18, v74, v18, v21
	v_mov_b32_dpp v9, v45 row_ror:2 row_mask:0xf bank_mask:0xf
	v_fma_f32 v18, v70, v19, v18
	v_fma_f32 v19, v83, v45, v87
	v_cndmask_b32_e64 v17, v17, v9, s[10:11]
	v_fma_f32 v16, v75, v16, v19
	s_nop 0
	v_fma_f32 v16, v71, v17, v16
	s_and_saveexec_b64 s[0:1], s[84:85]
	s_cbranch_execz .LBB0_932
	v_mul_f32_e32 v17, 0xbfb8aa3b, v23
	v_exp_f32_e32 v17, v17
	v_mul_f32_e32 v19, 0xbfb8aa3b, v34
	v_mul_f32_e32 v21, 0xbfb8aa3b, v36
	v_exp_f32_e32 v19, v19
	v_add_f32_e32 v17, 1.0, v17
	v_rcp_f32_e32 v17, v17
	v_exp_f32_e32 v21, v21
	v_add_f32_e32 v19, 1.0, v19
	v_rcp_f32_e32 v19, v19
	v_mul_f32_e32 v17, v23, v17
	v_mul_f32_e32 v17, v17, v16
	v_mul_f32_e32 v16, 0xbfb8aa3b, v38
	v_exp_f32_e32 v16, v16
	v_add_f32_e32 v21, 1.0, v21
	v_rcp_f32_e32 v21, v21
	v_mul_f32_e32 v19, v34, v19
	v_add_f32_e32 v16, 1.0, v16
	v_rcp_f32_e32 v16, v16
	v_mul_f32_e32 v18, v19, v18
	v_mul_f32_e32 v19, v36, v21
	v_mul_f32_e32 v19, v19, v20
	v_mul_f32_e32 v16, v38, v16
	v_mul_f32_e32 v16, v16, v22
	v_cvt_pk_bf16_f32 v16, v16, v19
	v_cvt_pk_bf16_f32 v17, v18, v17
	v_mov_b64_e32 v[18:19], s[36:37]
	v_mad_i64_i32 v[18:19], s[64:65], v114, s69, v[18:19]
	v_lshl_add_u64 v[18:19], v[192:193], 1, v[18:19]
	global_store_dwordx2 v[18:19], v[16:17], off offset:8
; __device__ __forceinline__ unsigned cvt_pk_bf16(float lo, float hi) { unsigned r; asm volatile("v_cvt_pk_bf16_f32 %0, %1, %2" : "=v"(r) : "v"(lo), "v"(hi)); return r; }
; __device__ __forceinline__ float sigmoid_f(float x) { return __builtin_amdgcn_rcpf(1.0f + __builtin_amdgcn_exp2f(-1.4426950408889634f * x)); }
; __device__ __forceinline__ float dpp_ror1(float v) { return __builtin_bit_cast(float, __builtin_amdgcn_update_dpp(0, __builtin_bit_cast(int, v), 0x121, 0xf, 0xf, false)); }
; __device__ __forceinline__ float dpp_ror2(float v) { return __builtin_bit_cast(float, __builtin_amdgcn_update_dpp(0, __builtin_bit_cast(int, v), 0x122, 0xf, 0xf, false)); }
; __device__ __forceinline__ float fma_s(float a, float b, float c) { float r; asm("v_fma_f32 %0, %1, %2, %3" : "=v"(r) : "v"(a), "v"(b), "v"(c)); return r; }
;     __device__ __forceinline__ void operator()(const f32x4 (&acc)[2][2][4][2], const Unit& u, int wr, int wc, int fr, int fq) const {
;     ...
;                 for (int m = 0; m < 4; ++m) {
;                     f32x4 cur[2] = {acc[ai][0][m][n] * r2v[ai][m], acc[ai][1][m][n] * r2v[ai][m]};
;                     if (first && ai == 0 && wr == 0 && m == 0 && fr < 2) { cur[0] = zero4; cur[1] = zero4; }
;                     f32x4 r1[2], r2[2], av[2];
; #pragma unroll
;                     for (int bj = 0; bj < 2; ++bj)
; #pragma unroll
;                         for (int e = 0; e < 4; ++e) { r1[bj][e] = dpp_ror1(cur[bj][e]); r2[bj][e] = dpp_ror2(cur[bj][e]); }
; #pragma unroll
;                     for (int bj = 0; bj < 2; ++bj)
; #pragma unroll
;                         for (int e = 0; e < 4; ++e) { const float p1 = fr >= 1 ? r1[bj][e] : pr1[bj][e], p2 = fr >= 2 ? r2[bj][e] : pr2[bj][e];
;                             av[bj][e] = fma_s(w0[bj][e], p2, fma_s(w1[bj][e], p1, fma_s(w2[bj][e], cur[bj][e], bb[bj][e]))); }
;                     float o[4];
; #pragma unroll
;                     for (int e = 0; e < 4; ++e) o[e] = av[0][e] * sigmoid_f(av[0][e]) * av[1][e];
;                     const int lr = ai * HALF + wr * 64 + m * 16 + fr, t = t0 + lr;
;                     if (lr >= 2 && t < 4096) { u32x2 w; w.x = cvt_pk_bf16(o[0], o[1]); w.y = cvt_pk_bf16(o[2], o[3]);
;                         *(u32x2*)(gout + (size_t)(b * 4096 + t) * FF + j0 + n * 4) = w; }
;                     pr1[0] = r1[0]; pr1[1] = r1[1]; pr2[0] = r2[0]; pr2[1] = r2[1];
.LBB0_932:
	s_or_b64 exec, exec, s[0:1]
	v_mov_b32_e32 v195, v194
	v_pk_mul_f32 v[4:5], v[4:5], v[194:195]
	v_pk_mul_f32 v[18:19], v[0:1], v[194:195]
	v_mov_b32_e32 v16, v194
	v_mov_b32_e32 v17, v194
	v_mov_b32_dpp v0, v4 row_ror:1 row_mask:0xf bank_mask:0xf
	v_pk_mul_f32 v[6:7], v[6:7], v[16:17]
	v_pk_mul_f32 v[16:17], v[2:3], v[16:17]
	v_mov_b32_dpp v1, v4 row_ror:2 row_mask:0xf bank_mask:0xf
	v_cndmask_b32_e64 v0, v0, v30, s[8:9]
	v_mov_b32_dpp v2, v5 row_ror:1 row_mask:0xf bank_mask:0xf
	v_cndmask_b32_e64 v1, v31, v1, s[10:11]
	v_fma_f32 v4, v96, v4, v100
	v_mov_b32_dpp v3, v5 row_ror:2 row_mask:0xf bank_mask:0xf
	v_fma_f32 v0, v92, v0, v4
	v_fma_f32 v0, v88, v1, v0
	v_cndmask_b32_e64 v1, v2, v28, s[8:9]
	v_mov_b32_dpp v20, v6 row_ror:1 row_mask:0xf bank_mask:0xf
	v_cndmask_b32_e64 v2, v29, v3, s[10:11]
	v_fma_f32 v3, v97, v5, v101
	v_mov_b32_dpp v21, v6 row_ror:2 row_mask:0xf bank_mask:0xf
	v_fma_f32 v1, v93, v1, v3
	v_fma_f32 v1, v89, v2, v1
	v_cndmask_b32_e64 v2, v20, v26, s[8:9]
	v_mov_b32_dpp v22, v7 row_ror:1 row_mask:0xf bank_mask:0xf
	v_cndmask_b32_e64 v3, v27, v21, s[10:11]
	v_fma_f32 v4, v98, v6, v102
	v_mov_b32_dpp v23, v7 row_ror:2 row_mask:0xf bank_mask:0xf
	v_fma_f32 v2, v94, v2, v4
	v_fma_f32 v2, v90, v3, v2
	v_cndmask_b32_e64 v3, v22, v15, s[8:9]
	v_mov_b32_dpp v32, v18 row_ror:1 row_mask:0xf bank_mask:0xf
	v_cndmask_b32_e64 v4, v25, v23, s[10:11]
	v_fma_f32 v5, v99, v7, v103
	v_mov_b32_dpp v33, v18 row_ror:2 row_mask:0xf bank_mask:0xf
	v_fma_f32 v3, v95, v3, v5
	v_fma_f32 v4, v91, v4, v3
	v_cndmask_b32_e64 v3, v32, v14, s[8:9]
	v_mov_b32_dpp v34, v19 row_ror:1 row_mask:0xf bank_mask:0xf
	v_cndmask_b32_e64 v5, v24, v33, s[10:11]
	v_fma_f32 v6, v80, v18, v84
	v_mov_b32_dpp v35, v19 row_ror:2 row_mask:0xf bank_mask:0xf
	v_fma_f32 v3, v72, v3, v6
	v_fma_f32 v3, v68, v5, v3
	v_cndmask_b32_e64 v5, v34, v12, s[8:9]
	v_mov_b32_dpp v36, v16 row_ror:1 row_mask:0xf bank_mask:0xf
	v_cndmask_b32_e64 v6, v13, v35, s[10:11]
	v_fma_f32 v7, v81, v19, v85
	v_mov_b32_dpp v37, v16 row_ror:2 row_mask:0xf bank_mask:0xf
	v_fma_f32 v5, v73, v5, v7
	v_fma_f32 v5, v69, v6, v5
	v_cndmask_b32_e64 v6, v36, v10, s[8:9]
	v_mov_b32_dpp v38, v17 row_ror:1 row_mask:0xf bank_mask:0xf
	v_cndmask_b32_e64 v7, v11, v37, s[10:11]
	v_fma_f32 v10, v82, v16, v86
	v_mov_b32_dpp v39, v17 row_ror:2 row_mask:0xf bank_mask:0xf
	v_fma_f32 v6, v74, v6, v10
	s_nop 0
	v_fma_f32 v6, v70, v7, v6
	v_cndmask_b32_e64 v7, v38, v8, s[8:9]
	v_cndmask_b32_e64 v8, v9, v39, s[10:11]
	v_fma_f32 v9, v83, v17, v87
	s_nop 0
	v_fma_f32 v7, v75, v7, v9
	s_nop 0
	v_fma_f32 v7, v71, v8, v7
	s_and_saveexec_b64 s[0:1], s[86:87]
	s_cbranch_execz .LBB0_934
	v_mul_f32_e32 v8, 0xbfb8aa3b, v4
	v_exp_f32_e32 v8, v8
	v_mul_f32_e32 v9, 0xbfb8aa3b, v2
	v_mul_f32_e32 v10, 0xbfb8aa3b, v1
	v_exp_f32_e32 v9, v9
	v_add_f32_e32 v8, 1.0, v8
	v_rcp_f32_e32 v8, v8
	v_exp_f32_e32 v10, v10
	v_add_f32_e32 v9, 1.0, v9
	v_rcp_f32_e32 v9, v9
	v_mul_f32_e32 v4, v4, v8
	v_mul_f32_e32 v4, v4, v7
	v_mul_f32_e32 v7, 0xbfb8aa3b, v0
	v_exp_f32_e32 v7, v7
	v_add_f32_e32 v8, 1.0, v10
	v_rcp_f32_e32 v8, v8
	v_mul_f32_e32 v2, v2, v9
	v_add_f32_e32 v7, 1.0, v7
	v_rcp_f32_e32 v7, v7
	v_mul_f32_e32 v1, v1, v8
	v_mul_f32_e32 v2, v2, v6
	v_mul_f32_e32 v1, v1, v5
	v_mul_f32_e32 v0, v0, v7
	v_mul_f32_e32 v0, v0, v3
	v_cvt_pk_bf16_f32 v0, v0, v1
	v_cvt_pk_bf16_f32 v1, v2, v4
	v_mov_b64_e32 v[2:3], s[36:37]
	v_mad_i64_i32 v[2:3], s[64:65], v115, s69, v[2:3]
	v_lshl_add_u64 v[2:3], v[192:193], 1, v[2:3]
	global_store_dwordx2 v[2:3], v[0:1], off offset:8
